# attention tile loop: K/k_pe/V staged by LDS-DMA a tile ahead with ONE s_barrier per KV tile (was two) + wave-half ping-pong order + QK^T read-ahead, on v021
# speedup vs baseline: 1.0040x; 1.0040x over previous
.LBB0_735:
	s_mov_b32 s68, s78
	s_mov_b64 s[0:1], 0
	v_mbcnt_lo_u32_b32 v137, -1, 0
	v_mbcnt_hi_u32_b32 v137, -1, v137
	s_add_u32 s40, s62, s0
	s_addc_u32 s41, s63, s1
	s_add_u32 s24, s40, 0x2f800000
	s_addc_u32 s25, s41, 0
	s_add_u32 s52, s40, 0x800000
	s_addc_u32 s53, s41, 0
	s_add_u32 s4, s40, 0x880000
	s_addc_u32 s5, s41, 0
	v_sub_co_u32_e64 v0, s[2:3], s42, 1
	s_and_b64 s[2:3], s[2:3], exec
	v_readfirstlane_b32 s2, v0
	s_cselect_b32 s10, 2, s2
	s_and_b64 s[2:3], s[34:35], exec
	s_cselect_b32 s2, s42, s10
	s_cmp_lg_u32 s2, 2
	s_mov_b64 s[16:17], -1
	s_cbranch_scc0 .LBB0_761
	s_andn2_b64 vcc, exec, s[54:55]
	s_cbranch_vccnz .LBB0_760
	s_cmp_eq_u32 s2, 0
	s_cselect_b32 s2, s15, s9
	s_lshl_b32 s14, s2, 8
	v_mbcnt_lo_u32_b32 v56, -1, 0
	v_mbcnt_hi_u32_b32 v56, -1, v56
	s_add_i32 s3, s14, s13
	v_and_b32_e32 v158, 31, v56
	v_or_b32_e32 v96, s3, v158
	v_lshl_add_u64 v[16:17], s[36:37], 0, v[96:97]
	v_mov_b64_e32 v[18:19], s[40:41]
	s_movk_i32 s3, 0xc00
	v_mad_u64_u32 v[18:19], s[16:17], v16, s3, v[18:19]
	v_readlane_b32 s16, v253, 43
	v_readlane_b32 s17, v253, 44
	v_bfe_u32 v159, v56, 5, 1
	v_mad_i32_i24 v19, v17, s3, v19
	s_mov_b32 s17, s80
	v_lshlrev_b64 v[0:1], 7, v[96:97]
	v_lshl_add_u64 v[16:17], v[18:19], 0, s[16:17]
	v_lshlrev_b32_e32 v130, 4, v159
	v_mov_b32_e32 v131, v97
	v_lshl_add_u64 v[2:3], s[52:53], 0, v[0:1]
	v_and_b32_e32 v96, 32, v56
	s_mov_b32 s10, s16
	v_lshl_add_u64 v[26:27], v[16:17], 0, v[130:131]
	s_mov_b64 s[16:17], 0x2ff00000
	v_lshl_add_u64 v[24:25], v[2:3], 0, v[96:97]
	v_lshl_add_u64 v[0:1], s[4:5], 0, v[0:1]
	v_lshl_add_u64 v[30:31], v[26:27], 0, s[16:17]
	v_lshl_add_u64 v[28:29], v[0:1], 0, v[96:97]
	global_load_dwordx4 v[0:3], v[24:25], off
	global_load_dwordx4 v[4:7], v[28:29], off
	global_load_dwordx4 v[8:11], v[24:25], off offset:16
	global_load_dwordx4 v[12:15], v[28:29], off offset:16
	global_load_dwordx4 v[16:19], v[30:31], off offset:320
	global_load_dwordx4 v[20:23], v[30:31], off offset:256
	s_mov_b32 s3, 0x2ff00000
	v_add_co_u32_e32 v26, vcc, s3, v26
	v_and_b32_e32 v131, 63, v56
	s_nop 0
	v_addc_co_u32_e32 v27, vcc, 0, v27, vcc
	global_load_dwordx4 v[126:129], v[26:27], off
	global_load_dwordx4 v[98:101], v[30:31], off offset:224
	global_load_dwordx4 v[122:125], v[30:31], off offset:32
	global_load_dwordx4 v[118:121], v[30:31], off offset:64
	global_load_dwordx4 v[114:117], v[30:31], off offset:96
	global_load_dwordx4 v[110:113], v[30:31], off offset:128
	global_load_dwordx4 v[106:109], v[30:31], off offset:160
	global_load_dwordx4 v[102:105], v[30:31], off offset:192
	v_lshlrev_b32_e32 v57, 4, v131
	v_add_u32_e32 v163, s20, v57
	v_writelane_b32 v253, s10, 43
	s_add_u32 s3, s40, s46
	v_or_b32_e32 v58, 32, v130
	v_writelane_b32 v253, s11, 44
	s_addc_u32 s10, s41, s47
	v_readlane_b32 s12, v253, 38
	s_add_u32 s3, s3, s12
	s_addc_u32 s10, s10, 0
	s_add_u32 s16, s3, 0x33000000
	s_addc_u32 s17, s10, 0
	v_or_b32_e32 v59, 64, v130
	v_or_b32_e32 v62, 0x60, v130
	v_lshlrev_b32_e32 v63, 7, v158
	s_mov_b32 s81, s80
	s_mov_b32 s82, s80
	s_mov_b32 s83, s80
	s_mov_b32 s84, s80
	s_mov_b32 s85, s80
	s_mov_b32 s86, s80
	s_mov_b32 s87, s80
	s_mov_b32 s88, s80
	s_mov_b32 s89, s80
	s_mov_b32 s90, s80
	s_mov_b32 s91, s80
	s_mov_b32 s92, s80
	s_mov_b32 s93, s80
	s_mov_b32 s94, s80
	s_mov_b32 s95, s80
	s_mov_b32 s26, 2
	v_cmp_gt_u32_e64 s[38:39], 32, v131
	v_lshl_add_u32 v160, v158, 2, s19
	v_mov_b32_e32 v161, 0
	s_waitcnt vmcnt(13)
	v_mov_b32_e32 v33, v0
	s_waitcnt vmcnt(12)
	v_mov_b32_e32 v27, v4
	v_mov_b32_e32 v32, v4
	v_mov_b32_e32 v4, v1
	s_waitcnt vmcnt(9)
	v_lshlrev_b32_e32 v43, 16, v16
	s_waitcnt vmcnt(8)
	v_lshlrev_b32_e32 v42, 16, v20
	v_and_b32_e32 v45, 0xffff0000, v16
	v_and_b32_e32 v44, 0xffff0000, v20
	v_mov_b32_e32 v26, v0
	v_mov_b32_e32 v0, v5
	v_mov_b32_e32 v34, v2
	v_mov_b32_e32 v35, v6
	v_mov_b32_e32 v37, v2
	v_mov_b32_e32 v2, v7
	v_lshlrev_b32_e32 v47, 16, v17
	v_lshlrev_b32_e32 v46, 16, v21
	v_and_b32_e32 v17, 0xffff0000, v17
	v_and_b32_e32 v16, 0xffff0000, v21
	v_pk_mul_f32 v[32:33], v[32:33], v[42:43]
	v_pk_mul_f32 v[4:5], v[4:5], v[44:45]
	v_mov_b32_e32 v36, v6
	v_mov_b32_e32 v6, v3
	v_mov_b32_e32 v39, v12
	v_mov_b32_e32 v40, v12
	v_pk_mul_f32 v[26:27], v[26:27], v[42:43]
	v_pk_mul_f32 v[0:1], v[0:1], v[44:45]
	v_pk_mul_f32 v[34:35], v[34:35], v[46:47]
	v_pk_mul_f32 v[2:3], v[2:3], v[16:17]
	v_add_f32_e32 v12, v32, v33
	v_sub_f32_e32 v4, v4, v5
	v_mov_b32_e32 v38, v8
	v_mov_b32_e32 v41, v8
	v_lshlrev_b32_e32 v21, 16, v18
	v_lshlrev_b32_e32 v20, 16, v22
	v_and_b32_e32 v49, 0xffff0000, v18
	v_and_b32_e32 v48, 0xffff0000, v22
	v_pk_mul_f32 v[36:37], v[36:37], v[46:47]
	v_pk_mul_f32 v[6:7], v[6:7], v[16:17]
	v_sub_f32_e32 v8, v26, v27
	v_add_f32_e32 v1, v0, v1
	v_sub_f32_e32 v5, v34, v35
	v_add_f32_e32 v2, v2, v3
	v_cvt_pk_bf16_f32 v0, v8, v4
	v_cvt_pk_bf16_f32 v4, v12, v1
	v_mov_b32_e32 v12, v9
	v_pk_mul_f32 v[16:17], v[38:39], v[20:21]
	v_add_f32_e32 v18, v36, v37
	v_sub_f32_e32 v6, v6, v7
	v_cvt_pk_bf16_f32 v1, v5, v6
	v_cvt_pk_bf16_f32 v5, v18, v2
	v_pk_mul_f32 v[2:3], v[12:13], v[48:49]
	v_sub_f32_e32 v7, v16, v17
	v_sub_f32_e32 v2, v2, v3
	v_mov_b32_e32 v8, v13
	v_cvt_pk_bf16_f32 v2, v7, v2
	v_pk_mul_f32 v[6:7], v[8:9], v[48:49]
	v_lshlrev_b32_e32 v9, 16, v19
	v_lshlrev_b32_e32 v8, 16, v23
	v_mov_b32_e32 v12, v10
	v_mov_b32_e32 v13, v14
	v_pk_mul_f32 v[20:21], v[40:41], v[20:21]
	v_add_f32_e32 v3, v6, v7
	v_pk_mul_f32 v[12:13], v[12:13], v[8:9]
	v_add_f32_e32 v16, v20, v21
	v_cvt_pk_bf16_f32 v6, v16, v3
	v_sub_f32_e32 v3, v12, v13
	v_mov_b32_e32 v12, v14
	v_mov_b32_e32 v13, v10
	v_pk_mul_f32 v[8:9], v[12:13], v[8:9]
	v_mov_b32_e32 v14, v11
	v_add_f32_e32 v7, v8, v9
	v_and_b32_e32 v9, 0xffff0000, v19
	v_and_b32_e32 v8, 0xffff0000, v23
	v_pk_mul_f32 v[12:13], v[14:15], v[8:9]
	v_add_u32_e32 v40, s18, v56
	v_sub_f32_e32 v10, v12, v13
	v_cvt_pk_bf16_f32 v3, v3, v10
	v_mov_b32_e32 v10, v15
	v_pk_mul_f32 v[8:9], v[10:11], v[8:9]
	s_nop 0
	v_add_f32_e32 v8, v8, v9
	v_cvt_pk_bf16_f32 v7, v7, v8
	global_load_dwordx4 v[8:11], v[30:31], off offset:352
	global_load_dwordx4 v[12:15], v[30:31], off offset:288
	global_load_dwordx4 v[16:19], v[24:25], off offset:64
	global_load_dwordx4 v[20:23], v[28:29], off offset:64
	s_nop 0
	global_load_dwordx4 v[24:27], v[24:25], off offset:80
	s_nop 0
	global_load_dwordx4 v[28:31], v[28:29], off offset:80
	ds_write_b128 v163, v[0:3]
	ds_write_b128 v163, v[4:7] offset:2048
	s_waitcnt vmcnt(5)
	v_lshlrev_b32_e32 v1, 16, v8
	s_waitcnt vmcnt(4)
	v_lshlrev_b32_e32 v0, 16, v12
	s_waitcnt vmcnt(3)
	v_mov_b32_e32 v2, v16
	s_waitcnt vmcnt(2)
	v_mov_b32_e32 v3, v20
	v_mov_b32_e32 v4, v20
	v_mov_b32_e32 v5, v16
	v_and_b32_e32 v7, 0xffff0000, v8
	v_and_b32_e32 v6, 0xffff0000, v12
	v_mov_b32_e32 v20, v17
	v_mov_b32_e32 v16, v21
	v_lshlrev_b32_e32 v33, 16, v9
	v_lshlrev_b32_e32 v32, 16, v13
	v_mov_b32_e32 v34, v18
	v_mov_b32_e32 v35, v22
	v_mov_b32_e32 v36, v22
	v_mov_b32_e32 v37, v18
	v_and_b32_e32 v9, 0xffff0000, v9
	v_and_b32_e32 v8, 0xffff0000, v13
	v_mov_b32_e32 v22, v19
	v_mov_b32_e32 v18, v23
	v_pk_mul_f32 v[2:3], v[2:3], v[0:1]
	v_pk_mul_f32 v[0:1], v[4:5], v[0:1]
	v_pk_mul_f32 v[4:5], v[20:21], v[6:7]
	v_pk_mul_f32 v[6:7], v[16:17], v[6:7]
	v_lshlrev_b32_e32 v13, 16, v10
	v_lshlrev_b32_e32 v12, 16, v14
	s_waitcnt vmcnt(1)
	v_mov_b32_e32 v38, v24
	v_pk_mul_f32 v[16:17], v[34:35], v[32:33]
	v_pk_mul_f32 v[22:23], v[22:23], v[8:9]
	v_pk_mul_f32 v[8:9], v[18:19], v[8:9]
	v_sub_f32_e32 v2, v2, v3
	v_add_f32_e32 v1, v0, v1
	v_sub_f32_e32 v0, v4, v5
	v_add_f32_e32 v3, v6, v7
	s_waitcnt vmcnt(0)
	v_mov_b32_e32 v39, v28
	v_pk_mul_f32 v[20:21], v[36:37], v[32:33]
	v_sub_f32_e32 v5, v16, v17
	v_add_f32_e32 v8, v8, v9
	v_cvt_pk_bf16_f32 v0, v2, v0
	v_cvt_pk_bf16_f32 v4, v1, v3
	v_pk_mul_f32 v[2:3], v[38:39], v[12:13]
	v_add_f32_e32 v6, v20, v21
	v_sub_f32_e32 v7, v22, v23
	v_cvt_pk_bf16_f32 v1, v5, v7
	v_cvt_pk_bf16_f32 v5, v6, v8
	v_sub_f32_e32 v8, v2, v3
	v_mov_b32_e32 v2, v28
	v_mov_b32_e32 v3, v24
	v_pk_mul_f32 v[2:3], v[2:3], v[12:13]
	v_and_b32_e32 v7, 0xffff0000, v10
	v_and_b32_e32 v6, 0xffff0000, v14
	v_mov_b32_e32 v28, v25
	v_add_f32_e32 v9, v2, v3
	v_pk_mul_f32 v[2:3], v[28:29], v[6:7]
	v_mov_b32_e32 v24, v29
	v_sub_f32_e32 v2, v2, v3
	v_pk_mul_f32 v[6:7], v[24:25], v[6:7]
	v_cvt_pk_bf16_f32 v2, v8, v2
	v_lshlrev_b32_e32 v8, 16, v15
	v_add_f32_e32 v3, v6, v7
	v_cvt_pk_bf16_f32 v6, v9, v3
	v_lshlrev_b32_e32 v9, 16, v11
	v_mov_b32_e32 v12, v26
	v_mov_b32_e32 v13, v30
	v_pk_mul_f32 v[12:13], v[12:13], v[8:9]
	v_ashrrev_i32_e32 v20, 4, v40
	v_sub_f32_e32 v3, v12, v13
	v_mov_b32_e32 v12, v30
	v_mov_b32_e32 v13, v26
	v_pk_mul_f32 v[8:9], v[12:13], v[8:9]
	v_mov_b32_e32 v30, v27
	v_add_f32_e32 v7, v8, v9
	v_and_b32_e32 v9, 0xffff0000, v11
	v_and_b32_e32 v8, 0xffff0000, v15
	v_pk_mul_f32 v[10:11], v[30:31], v[8:9]
	v_mov_b32_e32 v26, v31
	v_sub_f32_e32 v10, v10, v11
	v_cvt_pk_bf16_f32 v3, v3, v10
	v_pk_mul_f32 v[8:9], v[26:27], v[8:9]
	v_lshlrev_b32_e32 v26, 3, v56
	v_add_f32_e32 v8, v8, v9
	v_cvt_pk_bf16_f32 v7, v7, v8
	ds_write_b128 v163, v[0:3] offset:1024
	ds_write_b128 v163, v[4:7] offset:3072
	v_and_b32_e32 v0, 0x78, v26
	v_ashrrev_i32_e32 v21, 31, v20
	v_lshlrev_b32_e32 v27, 1, v0
	v_lshlrev_b64 v[48:49], 12, v[20:21]
	v_or_b32_e32 v0, v48, v27
	v_mov_b32_e32 v1, v49
	s_waitcnt lgkmcnt(0)
	v_add_u32_e32 v22, 32, v20
	v_lshl_add_u64 v[52:53], s[16:17], 0, v[0:1]
	global_load_dwordx4 v[0:3], v[52:53], off offset:256
	v_ashrrev_i32_e32 v23, 31, v22
	v_lshlrev_b64 v[4:5], 12, v[22:23]
	v_or_b32_e32 v4, v4, v27
	v_ashrrev_i32_e32 v24, 3, v40
	v_lshl_add_u64 v[12:13], s[16:17], 0, v[4:5]
	s_add_u32 s16, s24, s48
	v_ashrrev_i32_e32 v25, 31, v24
	s_addc_u32 s17, s25, s49
	v_lshlrev_b64 v[50:51], 7, v[24:25]
	v_lshlrev_b32_e32 v18, 4, v56
	v_lshl_add_u64 v[16:17], s[16:17], 0, v[50:51]
	v_and_b32_e32 v96, 0x70, v18
	global_load_dwordx4 v[4:7], v[12:13], off offset:256
	global_load_dwordx4 v[8:11], v[52:53], off
	v_lshl_add_u64 v[54:55], v[16:17], 0, v[96:97]
	global_load_dwordx4 v[12:15], v[12:13], off
	v_and_b32_e32 v21, 0xfffff0, v20
	global_load_dwordx4 v[16:19], v[54:55], off
	v_lshlrev_b32_e32 v23, 1, v20
	v_and_or_b32 v21, v23, 8, v21
	v_lshrrev_b32_e32 v23, 1, v20
	v_lshrrev_b32_e32 v21, 1, v21
	v_bfe_u32 v25, v26, 5, 2
	v_and_b32_e32 v26, 3, v20
	v_or_b32_e32 v21, v21, v25
	v_and_or_b32 v23, v23, 4, v26
	v_lshlrev_b32_e32 v21, 9, v21
	v_lshlrev_b32_e32 v23, 6, v23
	v_and_b32_e32 v26, 48, v27
	v_or3_b32 v21, v21, v23, v26
	v_and_b32_e32 v28, 0xfffff0, v22
	v_lshlrev_b32_e32 v29, 1, v22
	v_add_u32_e32 v166, 0, v21
	v_and_or_b32 v28, v29, 8, v28
	s_waitcnt vmcnt(0)
	v_lshrrev_b32_e32 v28, 1, v28
	v_or_b32_e32 v25, v28, v25
	v_lshlrev_b32_e32 v25, 9, v25
	v_or3_b32 v23, v25, v23, v26
	s_cmp_lg_u32 0, -1
	s_cselect_b32 s3, 0, 0
	v_add_u32_e32 v167, 0, v23
	s_add_i32 s12, 0, 0x10000
	v_bitop3_b32 v178, v130, v63, v96 bitop3:0xde
	v_add_u32_e32 v179, s12, v178
	v_bitop3_b32 v180, v58, v63, v96 bitop3:0xde
	v_add_u32_e32 v181, s12, v180
	v_bitop3_b32 v182, v59, v63, v96 bitop3:0xde
	v_add_u32_e32 v183, s12, v182
	v_bitop3_b32 v184, v62, v63, v96 bitop3:0xde
	v_add_u32_e32 v185, s12, v184
	s_lshl_b32 s27, s2, 2
	s_mov_b32 s2, 0x40000
	s_mov_b64 s[16:17], 0x40000
	v_add_co_u32_e32 v66, vcc, s2, v52
	s_mov_b32 s2, 0x60000
	s_nop 0
	v_addc_co_u32_e32 v67, vcc, 0, v53, vcc
	s_add_i32 s10, s27, 4
	s_add_i32 s27, s27, s28
	s_waitcnt vmcnt(4)
	ds_write_b128 v166, v[0:3]
	v_lshlrev_b32_e32 v0, 8, v20
	v_and_b32_e32 v1, 0x70, v40
	v_bitop3_b32 v0, v27, v0, v1 bitop3:0xde
	v_add_u32_e32 v168, 0, v0
	v_lshlrev_b32_e32 v0, 8, v22
	v_bitop3_b32 v0, v0, v27, v1 bitop3:0xf6
	v_lshlrev_b32_e32 v1, 4, v24
	v_add_u32_e32 v169, 0, v0
	v_lshlrev_b32_e32 v0, 7, v24
	v_and_b32_e32 v1, 0x70, v1
	v_bitop3_b32 v75, v1, v0, v96 bitop3:0xde
	s_waitcnt vmcnt(3)
	ds_write_b128 v167, v[4:7]
	s_waitcnt vmcnt(2)
	ds_write_b128 v168, v[8:11] offset:32768
	v_add_u32_e32 v0, s12, v75
	v_lshlrev_b32_e32 v8, 8, v158
	s_waitcnt vmcnt(1)
	ds_write_b128 v169, v[12:15] offset:32768
	s_waitcnt vmcnt(0)
	ds_write_b128 v0, v[16:19]
	v_bitop3_b32 v0, v130, v8, v96 bitop3:0xde
	v_add_u32_e32 v170, 0, v0
	s_waitcnt lgkmcnt(0)
	s_barrier
	ds_read_b128 v[0:3], v170 offset:32768
	ds_read_b128 v[4:7], v170 offset:40960
	s_waitcnt lgkmcnt(1)
	v_mfma_f32_32x32x16_bf16 v[32:47], v[0:3], v[126:129], 0
	v_bitop3_b32 v0, v58, v8, v96 bitop3:0xde
	v_add_u32_e32 v171, 0, v0
	v_add_u32_e32 v187, 0, v75
	v_add_u32_e32 v188, 0x12000, v187
	s_waitcnt lgkmcnt(0)
	v_mfma_f32_32x32x16_bf16 v[16:31], v[4:7], v[126:129], 0
	ds_read_b128 v[0:3], v171 offset:32768
	ds_read_b128 v[4:7], v171 offset:40960
	s_waitcnt lgkmcnt(1)
	v_mfma_f32_32x32x16_bf16 v[32:47], v[0:3], v[122:125], v[32:47]
	v_bitop3_b32 v0, v59, v8, v96 bitop3:0xde
	v_add_u32_e32 v172, 0, v0
	s_waitcnt lgkmcnt(0)
	v_mfma_f32_32x32x16_bf16 v[16:31], v[4:7], v[122:125], v[16:31]
	ds_read_b128 v[0:3], v172 offset:32768
	ds_read_b128 v[4:7], v172 offset:40960
	s_waitcnt lgkmcnt(1)
	v_mfma_f32_32x32x16_bf16 v[32:47], v[0:3], v[118:121], v[32:47]
	v_bitop3_b32 v0, v62, v8, v96 bitop3:0xde
	v_add_u32_e32 v173, 0, v0
	s_waitcnt lgkmcnt(0)
	v_mfma_f32_32x32x16_bf16 v[16:31], v[4:7], v[118:121], v[16:31]
	ds_read_b128 v[0:3], v173 offset:32768
	ds_read_b128 v[4:7], v173 offset:40960
	s_waitcnt lgkmcnt(1)
	v_mfma_f32_32x32x16_bf16 v[32:47], v[0:3], v[114:117], v[32:47]
	v_or_b32_e32 v0, 0x80, v130
	v_bitop3_b32 v0, v0, v8, v96 bitop3:0xde
	v_add_u32_e32 v174, 0, v0
	s_waitcnt lgkmcnt(0)
	v_mfma_f32_32x32x16_bf16 v[16:31], v[4:7], v[114:117], v[16:31]
	ds_read_b128 v[0:3], v174 offset:32768
	ds_read_b128 v[4:7], v174 offset:40960
	s_waitcnt lgkmcnt(1)
	v_mfma_f32_32x32x16_bf16 v[32:47], v[0:3], v[110:113], v[32:47]
	v_or_b32_e32 v0, 0xa0, v130
	v_bitop3_b32 v0, v0, v8, v96 bitop3:0xde
	v_add_u32_e32 v175, 0, v0
	s_waitcnt lgkmcnt(0)
	v_mfma_f32_32x32x16_bf16 v[16:31], v[4:7], v[110:113], v[16:31]
	ds_read_b128 v[0:3], v175 offset:32768
	ds_read_b128 v[4:7], v175 offset:40960
	s_waitcnt lgkmcnt(1)
	v_mfma_f32_32x32x16_bf16 v[32:47], v[0:3], v[106:109], v[32:47]
	v_or_b32_e32 v0, 0xc0, v130
	v_bitop3_b32 v0, v0, v8, v96 bitop3:0xde
	v_add_u32_e32 v176, 0, v0
	s_waitcnt lgkmcnt(0)
	v_mfma_f32_32x32x16_bf16 v[16:31], v[4:7], v[106:109], v[16:31]
	ds_read_b128 v[0:3], v176 offset:32768
	ds_read_b128 v[4:7], v176 offset:40960
	s_waitcnt lgkmcnt(1)
	v_mfma_f32_32x32x16_bf16 v[32:47], v[0:3], v[102:105], v[32:47]
	v_or_b32_e32 v0, 0xe0, v130
	v_bitop3_b32 v0, v0, v8, v96 bitop3:0xde
	v_add_u32_e32 v177, 0, v0
	s_waitcnt lgkmcnt(0)
	v_mfma_f32_32x32x16_bf16 v[16:31], v[4:7], v[102:105], v[16:31]
	ds_read_b128 v[0:3], v177 offset:32768
	ds_read_b128 v[4:7], v177 offset:40960
	s_waitcnt lgkmcnt(1)
	v_mfma_f32_32x32x16_bf16 v[32:47], v[0:3], v[98:101], v[32:47]
	s_waitcnt lgkmcnt(0)
	v_mfma_f32_32x32x16_bf16 v[16:31], v[4:7], v[98:101], v[16:31]
	ds_read_b128 v[0:3], v179
	ds_read_b128 v[4:7], v163
	ds_read_b128 v[8:11], v179 offset:4096
	ds_read_b128 v[12:15], v163 offset:1024
	s_waitcnt lgkmcnt(2)
	v_mfma_f32_32x32x16_bf16 v[32:47], v[0:3], v[4:7], v[32:47]
	ds_read_b128 v[0:3], v181
	s_waitcnt lgkmcnt(2)
	v_mfma_f32_32x32x16_bf16 v[16:31], v[8:11], v[4:7], v[16:31]
	v_lshlrev_b32_e32 v8, 3, v131
	v_and_b32_e32 v4, 0xc0, v57
	v_and_or_b32 v9, v8, 24, v4
	ds_read_b128 v[4:7], v181 offset:4096
	s_waitcnt lgkmcnt(0)
	v_mfma_f32_32x32x16_bf16 v[16:31], v[4:7], v[12:15], v[16:31]
	ds_read_b128 v[4:7], v163 offset:2048
	v_mfma_f32_32x32x16_bf16 v[32:47], v[0:3], v[12:15], v[32:47]
	v_lshlrev_b32_e32 v0, 1, v56
	v_and_b32_e32 v0, 32, v0
	v_and_b32_e32 v1, 0x100, v8
	v_or3_b32 v57, v9, v0, v1
	ds_read_b128 v[0:3], v183
	ds_read_b128 v[8:11], v183 offset:4096
	ds_read_b128 v[58:61], v163 offset:3072
	ds_read_b128 v[62:65], v185 offset:4096
	s_waitcnt lgkmcnt(3)
	v_mfma_f32_32x32x16_bf16 v[32:47], v[0:3], v[4:7], v[32:47]
	ds_read_b128 v[0:3], v185
	v_add_u32_e32 v164, s3, v57
	s_waitcnt lgkmcnt(3)
	v_mfma_f32_32x32x16_bf16 v[16:31], v[8:11], v[4:7], v[16:31]
	s_waitcnt lgkmcnt(0)
	v_mfma_f32_32x32x16_bf16 v[32:47], v[0:3], v[58:61], v[32:47]
	v_mov_b64_e32 v[0:1], s[80:81]
	v_mov_b64_e32 v[14:15], s[94:95]
	v_mov_b64_e32 v[2:3], s[82:83]
	v_mov_b64_e32 v[4:5], s[84:85]
	v_mov_b64_e32 v[6:7], s[86:87]
	v_mov_b64_e32 v[8:9], s[88:89]
	v_mov_b64_e32 v[10:11], s[90:91]
	v_mfma_f32_32x32x16_bf16 v[16:31], v[62:65], v[58:61], v[16:31]
	s_nop 3
	v_max_f32_e32 v58, v33, v33
	v_max_f32_e32 v59, v32, v32
	v_max_f32_e32 v58, v59, v58
	v_max3_f32 v74, v58, v34, v35
	v_lshl_add_u64 v[58:59], v[52:53], 0, s[16:17]
	s_mov_b64 s[16:17], 0x60000
	v_lshl_add_u64 v[62:63], v[52:53], 0, s[16:17]
	v_add_co_u32_e32 v52, vcc, s2, v52
	s_movk_i32 s2, 0x2000
	s_nop 0
	v_addc_co_u32_e32 v53, vcc, 0, v53, vcc
	global_load_dwordx4 v[58:61], v[58:59], off offset:256
	s_nop 0
	global_load_dwordx4 v[62:65], v[62:63], off offset:256
	s_nop 0
	global_load_dwordx4 v[66:69], v[66:67], off
	s_nop 0
	global_load_dwordx4 v[70:73], v[52:53], off
	v_add_co_u32_e32 v52, vcc, s2, v54
	v_max3_f32 v74, v74, v36, v37
	s_nop 0
	v_addc_co_u32_e32 v53, vcc, 0, v55, vcc
	global_load_dwordx4 v[52:55], v[52:53], off
	v_max3_f32 v74, v74, v38, v39
	v_max3_f32 v74, v74, v40, v41
	v_max3_f32 v74, v74, v42, v43
	v_max3_f32 v74, v74, v44, v45
	v_max3_f32 v74, v74, v46, v47
	v_max3_f32 v74, v74, v16, v17
	v_max3_f32 v74, v74, v18, v19
	v_max3_f32 v74, v74, v20, v21
	v_max3_f32 v74, v74, v22, v23
	v_max3_f32 v74, v74, v24, v25
	v_max3_f32 v74, v74, v26, v27
	v_max3_f32 v74, v74, v28, v29
	v_max3_f32 v74, v74, v30, v31
	v_mov_b32_e32 v76, v74
	s_nop 1
	v_permlane32_swap_b32_e32 v74, v76
	v_max_f32_e32 v76, v76, v76
	v_max_f32_e32 v74, v74, v74
	v_max_f32_e32 v74, v74, v76
	v_add_f32_e32 v76, 0x7149f2ca, v74
	v_max_f32_e32 v74, 0xf149f2ca, v74
	v_cmp_ge_f32_e32 vcc, s21, v76
	v_sub_f32_e32 v76, 0xf149f2ca, v74
	v_mul_f32_e32 v76, 0x3dd53b94, v76
	v_exp_f32_e32 v76, v76
	s_cmp_eq_u64 vcc, exec
	s_cselect_b64 vcc, -1, 0
	v_cndmask_b32_e32 v165, v74, v207, vcc
	v_mul_f32_e32 v74, 0xbdd53b94, v165
	s_addk_i32 s3, 0x4000
	v_cndmask_b32_e64 v186, v76, 1.0, vcc
	v_mov_b32_e32 v76, v74
	v_pk_fma_f32 v[148:149], v[16:17], s[74:75], v[74:75] op_sel_hi:[1,0,0]
	v_add_u32_e32 v162, s3, v57
	v_and_b32_e32 v16, 7, v56
	v_readlane_b32 s2, v253, 11
	v_fmamk_f32 v32, v32, 0x3dd53b94, v74
	v_fmamk_f32 v33, v33, 0x3dd53b94, v74
	v_fmamk_f32 v34, v34, 0x3dd53b94, v74
	v_fmamk_f32 v35, v35, 0x3dd53b94, v74
	v_fmamk_f32 v36, v36, 0x3dd53b94, v74
	v_fmamk_f32 v37, v37, 0x3dd53b94, v74
	v_fmamk_f32 v38, v38, 0x3dd53b94, v74
	v_fmamk_f32 v39, v39, 0x3dd53b94, v74
	v_fmamk_f32 v40, v40, 0x3dd53b94, v74
	v_fmamk_f32 v41, v41, 0x3dd53b94, v74
	v_fmamk_f32 v42, v42, 0x3dd53b94, v74
	v_fmamk_f32 v43, v43, 0x3dd53b94, v74
	v_fmamk_f32 v44, v44, 0x3dd53b94, v74
	v_fmamk_f32 v45, v45, 0x3dd53b94, v74
	v_fmamk_f32 v46, v46, 0x3dd53b94, v74
	v_fmac_f32_e32 v76, 0x3dd53b94, v47
	v_lshl_or_b32 v50, v16, 4, v50
	v_readlane_b32 s3, v253, 12
	v_exp_f32_e32 v220, v32
	v_exp_f32_e32 v222, v33
	v_exp_f32_e32 v218, v34
	v_exp_f32_e32 v221, v35
	v_exp_f32_e32 v216, v36
	v_exp_f32_e32 v219, v37
	v_exp_f32_e32 v215, v38
	v_exp_f32_e32 v217, v39
	v_exp_f32_e32 v212, v40
	v_exp_f32_e32 v214, v41
	v_exp_f32_e32 v210, v42
	v_exp_f32_e32 v213, v43
	v_exp_f32_e32 v198, v44
	v_exp_f32_e32 v211, v45
	v_exp_f32_e32 v197, v46
	v_exp_f32_e32 v199, v76
	v_lshl_add_u64 v[132:133], s[2:3], 0, v[50:51]
	v_and_b32_e32 v16, 15, v56
	v_readlane_b32 s2, v253, 15
	s_waitcnt vmcnt(0)
	v_lshl_or_b32 v48, v16, 4, v48
	v_readlane_b32 s3, v253, 16
	v_mov_b64_e32 v[12:13], s[92:93]
	v_readlane_b32 s88, v254, 6
	v_readlane_b32 s90, v254, 4
	v_readlane_b32 s86, v254, 2
	v_readlane_b32 s92, v253, 57
	v_pk_fma_f32 v[142:143], v[30:31], s[74:75], v[74:75] op_sel_hi:[1,0,0]
	v_pk_fma_f32 v[150:151], v[28:29], s[74:75], v[74:75] op_sel_hi:[1,0,0]
	v_pk_fma_f32 v[152:153], v[26:27], s[74:75], v[74:75] op_sel_hi:[1,0,0]
	v_pk_fma_f32 v[138:139], v[24:25], s[74:75], v[74:75] op_sel_hi:[1,0,0]
	v_pk_fma_f32 v[140:141], v[22:23], s[74:75], v[74:75] op_sel_hi:[1,0,0]
	v_pk_fma_f32 v[144:145], v[20:21], s[74:75], v[74:75] op_sel_hi:[1,0,0]
	v_pk_fma_f32 v[146:147], v[18:19], s[74:75], v[74:75] op_sel_hi:[1,0,0]
	s_waitcnt vmcnt(4)
	ds_write_b128 v166, v[58:61] offset:16384
	s_waitcnt vmcnt(3)
	ds_write_b128 v167, v[62:65] offset:16384
	s_waitcnt vmcnt(2)
	ds_write_b128 v168, v[66:69] offset:49152
	s_waitcnt vmcnt(1)
	ds_write_b128 v169, v[70:73] offset:49152
	s_waitcnt vmcnt(0)
	ds_write_b128 v188, v[52:55]
	v_lshl_add_u64 v[134:135], s[2:3], 0, v[48:49]
	v_mov_b64_e32 v[62:63], v[14:15]
	v_mov_b64_e32 v[46:47], v[14:15]
	v_mov_b64_e32 v[30:31], v[14:15]
	s_mov_b64 s[82:83], 0x5000
	s_movk_i32 s85, 0x3000
	s_mov_b32 s84, 0x18000
	v_readlane_b32 s94, v254, 10
	v_readlane_b32 s89, v254, 7
	v_readlane_b32 s91, v254, 5
	v_readlane_b32 s87, v254, 3
	v_readlane_b32 s93, v253, 58
	v_readlane_b32 s95, v253, 54
	v_mov_b64_e32 v[60:61], v[12:13]
	v_mov_b64_e32 v[58:59], v[10:11]
	v_mov_b64_e32 v[56:57], v[8:9]
	v_mov_b64_e32 v[54:55], v[6:7]
	v_mov_b64_e32 v[52:53], v[4:5]
	v_mov_b64_e32 v[50:51], v[2:3]
	v_mov_b64_e32 v[48:49], v[0:1]
	v_mov_b64_e32 v[44:45], v[12:13]
	v_mov_b64_e32 v[42:43], v[10:11]
	v_mov_b64_e32 v[40:41], v[8:9]
	v_mov_b64_e32 v[38:39], v[6:7]
	v_mov_b64_e32 v[36:37], v[4:5]
	v_mov_b64_e32 v[34:35], v[2:3]
	v_mov_b64_e32 v[32:33], v[0:1]
	v_mov_b64_e32 v[28:29], v[12:13]
	v_mov_b64_e32 v[26:27], v[10:11]
	v_mov_b64_e32 v[24:25], v[8:9]
	v_mov_b64_e32 v[22:23], v[6:7]
	v_mov_b64_e32 v[20:21], v[4:5]
	v_mov_b64_e32 v[18:19], v[2:3]
	v_mov_b64_e32 v[16:17], v[0:1]
	s_waitcnt lgkmcnt(0)
	s_barrier
	v_mbcnt_lo_u32_b32 v64, -1, 0
	v_mbcnt_hi_u32_b32 v64, -1, v64
	s_and_b32 s2, s78, 1
	s_lshl_b32 s3, s2, 2
	v_lshrrev_b32_e32 v65, 4, v64
	v_and_b32_e32 v66, 15, v64
	v_add_u32_e32 v67, s3, v65
	v_xor_b32_e32 v66, v66, v67
	v_lshlrev_b32_e32 v66, 4, v66
	v_lshl_add_u32 v166, v65, 12, v66
	v_lshrrev_b32_e32 v65, 3, v64
	v_and_b32_e32 v66, 7, v64
	v_xor_b32_e32 v66, v66, v65
	v_lshlrev_b32_e32 v66, 4, v66
	v_lshl_add_u32 v168, v65, 7, v66
	v_bfe_u32 v65, v64, 4, 1
	v_bfe_u32 v66, v64, 2, 2
	v_lshl_add_u32 v65, v65, 3, v66
	v_lshrrev_b32_e32 v66, 5, v64
	v_and_b32_e32 v67, 3, v64
	v_lshlrev_b32_e32 v67, 4, v67
	v_lshl_add_u32 v66, v66, 6, v67
	v_lshl_add_u32 v167, v65, 12, v66
	s_bfe_u32 s2, s78, 0x10002
	s_lshl_b32 s2, s2, 16
	s_bfe_u32 s3, s78, 0x10001
	s_lshl_b32 s3, s3, 14
	s_add_u32 s2, s2, s3
	s_and_b32 s3, s78, 1
	s_lshl_b32 s3, s3, 7
	s_add_u32 s2, s2, s3
	v_add_u32_e32 v167, s2, v167
.LBB0_738:
	s_cmp_lt_u32 s78, 4
	s_cbranch_scc0 .Latt1_738
	v_readfirstlane_b32 s16, v134
	v_readfirstlane_b32 s17, v135
	s_lshl_b32 s3, s78, 10
	s_add_u32 s16, s16, 0x33080000
	s_addc_u32 s17, s17, 0
	s_add_i32 m0, s3, 0x8000
	s_nop 0
	global_load_lds_dwordx4 v166, s[16:17]
	s_add_u32 s16, s16, 0x20000
	s_addc_u32 s17, s17, 0
	s_add_i32 m0, s3, 0xa000
	s_nop 0
	global_load_lds_dwordx4 v166, s[16:17]
	v_readfirstlane_b32 s16, v132
	v_readfirstlane_b32 s17, v133
	s_add_u32 s16, s16, 0x2f804000
	s_addc_u32 s17, s17, 0
	s_add_i32 m0, s3, 0x10000
	s_nop 0
	global_load_lds_dwordx4 v168, s[16:17]
	v_readfirstlane_b32 s16, v134
	v_readfirstlane_b32 s17, v135
	s_lshl_b32 s3, s78, 14
	s_sub_u32 s16, s16, s3
	s_subb_u32 s17, s17, 0
	s_add_u32 s16, s16, 0x33040100
	s_addc_u32 s17, s17, 0
	s_lshl_b32 s3, s78, 10
	s_add_i32 m0, s3, 0x4000
	s_nop 0
	global_load_lds_dwordx4 v167, s[16:17]
	s_add_u32 s16, s16, 0x20000
	s_addc_u32 s17, s17, 0
	s_add_i32 m0, s3, 0x6000
	s_nop 0
	global_load_lds_dwordx4 v167, s[16:17]
	s_add_i32 s2, s26, -1
	ds_read_b128 v[64:67], v170 offset:49152
	ds_read_b128 v[68:71], v170 offset:57344
	ds_read_b128 v[154:157], v171 offset:49152
	ds_read_b128 v[190:193], v171 offset:57344
	ds_read_b128 v[202:205], v172 offset:49152
	ds_read_b128 v[224:227], v172 offset:57344
	s_add_i32 s3, 0, 0x12000
	v_add_u32_e32 v189, s3, v178
	s_cmp_gt_u32 s2, s27
	s_cselect_b64 vcc, -1, 0
	s_waitcnt lgkmcnt(5)
	v_mfma_f32_32x32x16_bf16 v[80:95], v[64:67], v[126:129], 0
	s_waitcnt lgkmcnt(4)
	v_mfma_f32_32x32x16_bf16 v[64:79], v[68:71], v[126:129], 0
	s_waitcnt lgkmcnt(3)
	v_mfma_f32_32x32x16_bf16 v[80:95], v[154:157], v[122:125], v[80:95]
	ds_read_b128 v[154:157], v173 offset:49152
	s_waitcnt lgkmcnt(3)
	v_mfma_f32_32x32x16_bf16 v[64:79], v[190:193], v[122:125], v[64:79]
	ds_read_b128 v[190:193], v173 offset:57344
	s_waitcnt lgkmcnt(3)
	v_mfma_f32_32x32x16_bf16 v[80:95], v[202:205], v[118:121], v[80:95]
	ds_read_b128 v[202:205], v174 offset:49152
	s_waitcnt lgkmcnt(3)
	v_mfma_f32_32x32x16_bf16 v[64:79], v[224:227], v[118:121], v[64:79]
	ds_read_b128 v[224:227], v174 offset:57344
	s_waitcnt lgkmcnt(3)
	v_mfma_f32_32x32x16_bf16 v[80:95], v[154:157], v[114:117], v[80:95]
	ds_read_b128 v[154:157], v175 offset:49152
	s_waitcnt lgkmcnt(3)
	v_mfma_f32_32x32x16_bf16 v[64:79], v[190:193], v[114:117], v[64:79]
	ds_read_b128 v[190:193], v175 offset:57344
	s_waitcnt lgkmcnt(3)
	v_mfma_f32_32x32x16_bf16 v[80:95], v[202:205], v[110:113], v[80:95]
	ds_read_b128 v[202:205], v176 offset:49152
	s_waitcnt lgkmcnt(3)
	v_mfma_f32_32x32x16_bf16 v[64:79], v[224:227], v[110:113], v[64:79]
	ds_read_b128 v[224:227], v176 offset:57344
	s_waitcnt lgkmcnt(3)
	v_mfma_f32_32x32x16_bf16 v[80:95], v[154:157], v[106:109], v[80:95]
	ds_read_b128 v[154:157], v177 offset:49152
	s_waitcnt lgkmcnt(3)
	v_mfma_f32_32x32x16_bf16 v[64:79], v[190:193], v[106:109], v[64:79]
	ds_read_b128 v[190:193], v177 offset:57344
	s_waitcnt lgkmcnt(3)
	v_mfma_f32_32x32x16_bf16 v[80:95], v[202:205], v[102:105], v[80:95]
	s_waitcnt lgkmcnt(2)
	v_mfma_f32_32x32x16_bf16 v[64:79], v[224:227], v[102:105], v[64:79]
	s_waitcnt lgkmcnt(1)
	v_mfma_f32_32x32x16_bf16 v[80:95], v[154:157], v[98:101], v[80:95]
	s_waitcnt lgkmcnt(0)
	v_mfma_f32_32x32x16_bf16 v[64:79], v[190:193], v[98:101], v[64:79]
	ds_read_b128 v[154:157], v189
	ds_read_b128 v[190:193], v189 offset:4096
	ds_read_b128 v[202:205], v163
	s_waitcnt lgkmcnt(0)
	v_mfma_f32_32x32x16_bf16 v[80:95], v[154:157], v[202:205], v[80:95]
	v_mfma_f32_32x32x16_bf16 v[64:79], v[190:193], v[202:205], v[64:79]
	v_add_u32_e32 v190, s3, v180
	ds_read_b128 v[154:157], v190
	ds_read_b128 v[192:195], v190 offset:4096
	ds_read_b128 v[202:205], v163 offset:1024
	v_add_u32_e32 v191, s3, v182
	s_waitcnt lgkmcnt(0)
	v_mfma_f32_32x32x16_bf16 v[80:95], v[154:157], v[202:205], v[80:95]
	v_mfma_f32_32x32x16_bf16 v[64:79], v[192:195], v[202:205], v[64:79]
	ds_read_b128 v[154:157], v191
	ds_read_b128 v[192:195], v191 offset:4096
	ds_read_b128 v[202:205], v163 offset:2048
	s_waitcnt lgkmcnt(0)
	v_mfma_f32_32x32x16_bf16 v[80:95], v[154:157], v[202:205], v[80:95]
	v_mfma_f32_32x32x16_bf16 v[64:79], v[192:195], v[202:205], v[64:79]
	v_add_u32_e32 v192, s3, v184
	ds_read_b128 v[154:157], v192
	ds_read_b128 v[202:205], v192 offset:4096
	ds_read_b128 v[224:227], v163 offset:3072
	s_waitcnt lgkmcnt(0)
	v_mfma_f32_32x32x16_bf16 v[80:95], v[154:157], v[224:227], v[80:95]
	v_mfma_f32_32x32x16_bf16 v[64:79], v[202:205], v[224:227], v[64:79]
	s_nop 10
	v_cndmask_b32_e32 v240, v80, v208, vcc
	v_add_f32_e32 v80, 0, v220
	v_add_f32_e32 v80, v222, v80
	v_add_f32_e32 v80, v218, v80
	v_add_f32_e32 v80, v221, v80
	v_add_f32_e32 v80, v216, v80
	v_add_f32_e32 v80, v219, v80
	v_add_f32_e32 v80, v215, v80
	v_add_f32_e32 v80, v217, v80
	v_add_f32_e32 v80, v212, v80
	v_add_f32_e32 v80, v214, v80
	v_add_f32_e32 v80, v210, v80
	v_add_f32_e32 v80, v213, v80
	v_cndmask_b32_e32 v244, v64, v208, vcc
	v_exp_f32_e32 v64, v148
	v_add_f32_e32 v80, v198, v80
	v_cndmask_b32_e32 v245, v65, v208, vcc
	v_exp_f32_e32 v65, v149
	v_add_f32_e32 v80, v211, v80
	v_cndmask_b32_e32 v242, v66, v208, vcc
	v_exp_f32_e32 v66, v146
	v_add_f32_e32 v80, v197, v80
	v_cndmask_b32_e32 v243, v67, v208, vcc
	v_exp_f32_e32 v67, v147
	v_add_f32_e32 v80, v199, v80
	v_cndmask_b32_e32 v238, v68, v208, vcc
	v_exp_f32_e32 v68, v144
	v_add_f32_e32 v80, v64, v80
	v_cndmask_b32_e32 v239, v69, v208, vcc
	v_exp_f32_e32 v69, v145
	v_add_f32_e32 v80, v65, v80
	v_cndmask_b32_e32 v234, v70, v208, vcc
	v_exp_f32_e32 v70, v140
	v_add_f32_e32 v80, v66, v80
	v_cndmask_b32_e32 v235, v71, v208, vcc
	v_exp_f32_e32 v71, v141
	v_add_f32_e32 v80, v67, v80
	v_cndmask_b32_e32 v230, v72, v208, vcc
	v_exp_f32_e32 v72, v138
	v_add_f32_e32 v80, v68, v80
	v_cndmask_b32_e32 v231, v73, v208, vcc
	v_exp_f32_e32 v73, v139
	v_add_f32_e32 v80, v69, v80
	v_cndmask_b32_e32 v227, v74, v208, vcc
	v_exp_f32_e32 v74, v152
	v_add_f32_e32 v80, v70, v80
	v_cndmask_b32_e32 v228, v75, v208, vcc
	v_exp_f32_e32 v75, v153
	v_add_f32_e32 v80, v71, v80
	v_cndmask_b32_e32 v225, v76, v208, vcc
	v_exp_f32_e32 v76, v150
	v_add_f32_e32 v80, v72, v80
	v_cndmask_b32_e32 v195, v90, v208, vcc
	v_cndmask_b32_e32 v90, v77, v208, vcc
	v_exp_f32_e32 v77, v151
	v_add_f32_e32 v80, v73, v80
	v_cndmask_b32_e32 v223, v88, v208, vcc
	v_cndmask_b32_e32 v88, v78, v208, vcc
	v_exp_f32_e32 v78, v142
	v_add_f32_e32 v80, v74, v80
	v_cndmask_b32_e32 v224, v89, v208, vcc
	v_cndmask_b32_e32 v89, v79, v208, vcc
	v_exp_f32_e32 v79, v143
	v_add_f32_e32 v80, v75, v80
	v_add_f32_e32 v80, v76, v80
	v_add_f32_e32 v80, v77, v80
	v_add_f32_e32 v80, v78, v80
	v_add_f32_e32 v193, v79, v80
	v_cndmask_b32_e32 v226, v86, v208, vcc
	v_cndmask_b32_e32 v232, v84, v208, vcc
	v_cndmask_b32_e32 v233, v85, v208, vcc
	v_mov_b32_e32 v194, v193
	v_cvt_pk_bf16_f32 v84, v220, v222
	v_cvt_pk_bf16_f32 v85, v218, v221
	v_cvt_pk_bf16_f32 v86, v216, v219
	v_cndmask_b32_e32 v94, v94, v208, vcc
	v_cndmask_b32_e32 v95, v95, v208, vcc
	v_cndmask_b32_e32 v92, v92, v208, vcc
	v_cndmask_b32_e32 v93, v93, v208, vcc
	v_cndmask_b32_e32 v91, v91, v208, vcc
	v_cndmask_b32_e32 v229, v87, v208, vcc
	v_cndmask_b32_e32 v236, v82, v208, vcc
	v_cndmask_b32_e32 v237, v83, v208, vcc
	v_cndmask_b32_e32 v241, v81, v208, vcc
	v_permlane32_swap_b32_e32 v193, v194
	v_cvt_pk_bf16_f32 v87, v215, v217
	v_permlane32_swap_b32_e32 v84, v86
	v_cvt_pk_bf16_f32 v142, v212, v214
	v_cvt_pk_bf16_f32 v143, v210, v213
	v_cvt_pk_bf16_f32 v144, v198, v211
	v_cvt_pk_bf16_f32 v145, v197, v199
	v_cvt_pk_bf16_f32 v146, v64, v65
	v_cvt_pk_bf16_f32 v147, v66, v67
	v_cvt_pk_bf16_f32 v148, v68, v69
	v_cvt_pk_bf16_f32 v149, v70, v71
	v_cvt_pk_bf16_f32 v150, v72, v73
	v_cvt_pk_bf16_f32 v151, v74, v75
	v_cvt_pk_bf16_f32 v152, v76, v77
	v_cvt_pk_bf16_f32 v153, v78, v79
	v_permlane32_swap_b32_e32 v85, v87
	v_permlane32_swap_b32_e32 v142, v144
	v_permlane32_swap_b32_e32 v143, v145
	v_permlane32_swap_b32_e32 v146, v148
	v_permlane32_swap_b32_e32 v147, v149
	v_permlane32_swap_b32_e32 v150, v152
	v_permlane32_swap_b32_e32 v151, v153
	ds_read_b64_tr_b16 v[154:155], v164 offset:0
	ds_read_b64_tr_b16 v[156:157], v164 offset:0x800
	ds_read_b64_tr_b16 v[196:197], v164 offset:0x1000
	ds_read_b64_tr_b16 v[198:199], v164 offset:0x1800
	ds_read_b64_tr_b16 v[202:203], v164 offset:0x2000
	ds_read_b64_tr_b16 v[204:205], v164 offset:0x2800
	ds_read_b64_tr_b16 v[210:211], v164 offset:0x3000
	ds_read_b64_tr_b16 v[212:213], v164 offset:0x3800
	s_waitcnt lgkmcnt(0)
	s_nop 0
	v_mfma_f32_32x32x16_bf16 v[0:15], v[84:87], v[154:157], v[0:15]
	ds_read_b64_tr_b16 v[154:155], v164 offset:0x200
	ds_read_b64_tr_b16 v[156:157], v164 offset:0xa00
	v_mfma_f32_32x32x16_bf16 v[0:15], v[142:145], v[196:199], v[0:15]
	ds_read_b64_tr_b16 v[196:197], v164 offset:0x1200
	ds_read_b64_tr_b16 v[198:199], v164 offset:0x1a00
	v_mfma_f32_32x32x16_bf16 v[0:15], v[146:149], v[202:205], v[0:15]
	ds_read_b64_tr_b16 v[202:203], v164 offset:0x2200
	ds_read_b64_tr_b16 v[204:205], v164 offset:0x2a00
	v_mfma_f32_32x32x16_bf16 v[0:15], v[150:153], v[210:213], v[0:15]
	ds_read_b64_tr_b16 v[210:211], v164 offset:0x3200
	ds_read_b64_tr_b16 v[212:213], v164 offset:0x3a00
	s_waitcnt lgkmcnt(0)
	v_mfma_f32_32x32x16_bf16 v[48:63], v[84:87], v[154:157], v[48:63]
	ds_read_b64_tr_b16 v[154:155], v164 offset:0x400
	ds_read_b64_tr_b16 v[156:157], v164 offset:0xc00
	v_mfma_f32_32x32x16_bf16 v[48:63], v[142:145], v[196:199], v[48:63]
	ds_read_b64_tr_b16 v[196:197], v164 offset:0x1400
	ds_read_b64_tr_b16 v[198:199], v164 offset:0x1c00
	v_mfma_f32_32x32x16_bf16 v[48:63], v[146:149], v[202:205], v[48:63]
	ds_read_b64_tr_b16 v[202:203], v164 offset:0x2400
	ds_read_b64_tr_b16 v[204:205], v164 offset:0x2c00
	v_mfma_f32_32x32x16_bf16 v[48:63], v[150:153], v[210:213], v[48:63]
	ds_read_b64_tr_b16 v[210:211], v164 offset:0x3400
	ds_read_b64_tr_b16 v[212:213], v164 offset:0x3c00
	s_waitcnt lgkmcnt(0)
	v_mfma_f32_32x32x16_bf16 v[32:47], v[84:87], v[154:157], v[32:47]
	ds_read_b64_tr_b16 v[154:155], v164 offset:0x600
	ds_read_b64_tr_b16 v[156:157], v164 offset:0xe00
	v_mfma_f32_32x32x16_bf16 v[32:47], v[142:145], v[196:199], v[32:47]
	ds_read_b64_tr_b16 v[196:197], v164 offset:0x1600
	ds_read_b64_tr_b16 v[198:199], v164 offset:0x1e00
	v_mfma_f32_32x32x16_bf16 v[32:47], v[146:149], v[202:205], v[32:47]
	ds_read_b64_tr_b16 v[202:203], v164 offset:0x2600
	ds_read_b64_tr_b16 v[204:205], v164 offset:0x2e00
	v_mfma_f32_32x32x16_bf16 v[32:47], v[150:153], v[210:213], v[32:47]
	ds_read_b64_tr_b16 v[210:211], v164 offset:0x3600
	ds_read_b64_tr_b16 v[212:213], v164 offset:0x3e00
	s_waitcnt lgkmcnt(0)
	v_mfma_f32_32x32x16_bf16 v[16:31], v[84:87], v[154:157], v[16:31]
	v_max_f32_e32 v84, v241, v241
	v_max_f32_e32 v85, v240, v240
	v_max_f32_e32 v84, v85, v84
	v_max3_f32 v84, v84, v236, v237
	v_max3_f32 v84, v84, v232, v233
	v_max3_f32 v84, v84, v226, v229
	v_max3_f32 v84, v84, v223, v224
	v_mfma_f32_32x32x16_bf16 v[16:31], v[142:145], v[196:199], v[16:31]
	v_max3_f32 v84, v84, v195, v91
	v_max3_f32 v84, v84, v92, v93
	v_max3_f32 v84, v84, v94, v95
	v_max3_f32 v84, v84, v244, v245
	v_max3_f32 v84, v84, v242, v243
	v_max3_f32 v84, v84, v238, v239
	v_max3_f32 v84, v84, v234, v235
	v_mfma_f32_32x32x16_bf16 v[16:31], v[146:149], v[202:205], v[16:31]
	v_max3_f32 v84, v84, v230, v231
	v_max3_f32 v84, v84, v227, v228
	v_max3_f32 v84, v84, v225, v90
	v_max3_f32 v84, v84, v88, v89
	v_mov_b32_e32 v85, v84
	s_nop 1
	v_permlane32_swap_b32_e32 v84, v85
	v_mfma_f32_32x32x16_bf16 v[16:31], v[150:153], v[210:213], v[16:31]
	v_max_f32_e32 v85, v85, v85
	v_max_f32_e32 v84, v84, v84
	v_max_f32_e32 v84, v84, v85
	v_sub_f32_e32 v85, v84, v165
	v_cmp_ge_f32_e32 vcc, s21, v85
	v_mov_b32_e32 v196, 1.0
	s_cmp_eq_u64 vcc, exec
	s_cbranch_scc0 .LBB0_750
.LBB0_739:
	v_cmp_gt_f32_e32 vcc, 1.0, v196
	s_cbranch_vccz .LBB0_743
	s_and_saveexec_b64 s[16:17], s[38:39]
	ds_write_b32 v160, v196 offset:128
	s_or_b64 exec, exec, s[16:17]
	s_waitcnt lgkmcnt(0)
	v_add_u32_e32 v76, s19, v130
	ds_read_b128 v[64:67], v76 offset:224
	ds_read_b128 v[68:71], v76 offset:192
	ds_read_b128 v[72:75], v76 offset:160
	ds_read_b128 v[76:79], v76 offset:128
	s_waitcnt lgkmcnt(3)
	v_pk_mul_f32 v[12:13], v[12:13], v[64:65]
	s_waitcnt lgkmcnt(2)
	v_pk_mul_f32 v[8:9], v[8:9], v[68:69]
	s_waitcnt lgkmcnt(1)
	v_pk_mul_f32 v[4:5], v[4:5], v[72:73]
	v_pk_mul_f32 v[14:15], v[14:15], v[66:67]
	v_pk_mul_f32 v[10:11], v[10:11], v[70:71]
	v_pk_mul_f32 v[6:7], v[6:7], v[74:75]
	s_waitcnt lgkmcnt(0)
	v_pk_mul_f32 v[2:3], v[2:3], v[78:79]
	v_pk_mul_f32 v[0:1], v[0:1], v[76:77]
	v_pk_mul_f32 v[60:61], v[60:61], v[64:65]
	v_pk_mul_f32 v[56:57], v[56:57], v[68:69]
	v_pk_mul_f32 v[52:53], v[52:53], v[72:73]
	v_pk_mul_f32 v[62:63], v[62:63], v[66:67]
	v_pk_mul_f32 v[58:59], v[58:59], v[70:71]
	v_pk_mul_f32 v[54:55], v[54:55], v[74:75]
	v_pk_mul_f32 v[50:51], v[50:51], v[78:79]
	v_pk_mul_f32 v[48:49], v[48:49], v[76:77]
	v_pk_mul_f32 v[44:45], v[44:45], v[64:65]
	v_pk_mul_f32 v[40:41], v[40:41], v[68:69]
	v_pk_mul_f32 v[36:37], v[36:37], v[72:73]
	v_pk_mul_f32 v[46:47], v[46:47], v[66:67]
	v_pk_mul_f32 v[42:43], v[42:43], v[70:71]
	v_pk_mul_f32 v[38:39], v[38:39], v[74:75]
	v_pk_mul_f32 v[34:35], v[34:35], v[78:79]
	v_pk_mul_f32 v[32:33], v[32:33], v[76:77]
	v_pk_mul_f32 v[28:29], v[28:29], v[64:65]
	v_pk_mul_f32 v[24:25], v[24:25], v[68:69]
	v_pk_mul_f32 v[20:21], v[20:21], v[72:73]
	v_pk_mul_f32 v[30:31], v[30:31], v[66:67]
	v_pk_mul_f32 v[26:27], v[26:27], v[70:71]
	v_pk_mul_f32 v[22:23], v[22:23], v[74:75]
	v_pk_mul_f32 v[18:19], v[18:19], v[78:79]
	v_pk_mul_f32 v[16:17], v[16:17], v[76:77]
.LBB0_743:
	v_mul_f32_e32 v136, 0xbdd53b94, v165
	v_fmamk_f32 v78, v94, 0x3dd53b94, v136
	v_fmamk_f32 v74, v195, 0x3dd53b94, v136
	v_exp_f32_e32 v195, v78
	v_fmamk_f32 v64, v240, 0x3dd53b94, v136
	v_fmamk_f32 v65, v241, 0x3dd53b94, v136
	v_fmamk_f32 v66, v236, 0x3dd53b94, v136
	v_fmamk_f32 v67, v237, 0x3dd53b94, v136
	v_fmamk_f32 v68, v232, 0x3dd53b94, v136
	v_fmamk_f32 v69, v233, 0x3dd53b94, v136
	v_fmamk_f32 v70, v226, 0x3dd53b94, v136
	v_fmamk_f32 v71, v229, 0x3dd53b94, v136
	v_fmamk_f32 v72, v223, 0x3dd53b94, v136
	v_fmamk_f32 v73, v224, 0x3dd53b94, v136
	v_fmamk_f32 v75, v91, 0x3dd53b94, v136
	v_fmamk_f32 v76, v92, 0x3dd53b94, v136
	v_fmamk_f32 v77, v93, 0x3dd53b94, v136
	v_fmamk_f32 v79, v95, 0x3dd53b94, v136
	v_fmamk_f32 v223, v244, 0x3dd53b94, v136
	v_fmamk_f32 v224, v245, 0x3dd53b94, v136
	v_fmamk_f32 v236, v242, 0x3dd53b94, v136
	v_fmamk_f32 v237, v243, 0x3dd53b94, v136
	v_fmamk_f32 v238, v238, 0x3dd53b94, v136
	v_fmamk_f32 v239, v239, 0x3dd53b94, v136
	v_fmamk_f32 v240, v234, 0x3dd53b94, v136
	v_fmamk_f32 v241, v235, 0x3dd53b94, v136
	v_fmamk_f32 v242, v230, 0x3dd53b94, v136
	v_fmamk_f32 v243, v231, 0x3dd53b94, v136
	v_fmamk_f32 v244, v227, 0x3dd53b94, v136
	v_fmamk_f32 v245, v228, 0x3dd53b94, v136
	v_fmamk_f32 v246, v225, 0x3dd53b94, v136
	v_exp_f32_e32 v233, v64
	v_exp_f32_e32 v235, v65
	v_exp_f32_e32 v231, v66
	v_exp_f32_e32 v234, v67
	v_exp_f32_e32 v229, v68
	v_exp_f32_e32 v232, v69
	v_exp_f32_e32 v228, v70
	v_exp_f32_e32 v230, v71
	v_exp_f32_e32 v225, v72
	v_exp_f32_e32 v227, v73
	v_exp_f32_e32 v221, v74
	v_exp_f32_e32 v226, v75
	v_exp_f32_e32 v219, v76
	v_exp_f32_e32 v222, v77
	v_exp_f32_e32 v220, v79
	v_fmamk_f32 v247, v90, 0x3dd53b94, v136
	v_fmamk_f32 v248, v88, 0x3dd53b94, v136
	v_fmamk_f32 v202, v89, 0x3dd53b94, v136
	s_waitcnt vmcnt(0) lgkmcnt(0)
	s_barrier
	v_readfirstlane_b32 s16, v134
	v_readfirstlane_b32 s17, v135
	s_lshl_b32 s3, s78, 10
	s_add_u32 s16, s16, 0x330c0000
	s_addc_u32 s17, s17, 0
	s_add_i32 m0, s3, 0xc000
	s_nop 0
	global_load_lds_dwordx4 v166, s[16:17]
	s_add_u32 s16, s16, 0x20000
	s_addc_u32 s17, s17, 0
	s_add_i32 m0, s3, 0xe000
	s_nop 0
	global_load_lds_dwordx4 v166, s[16:17]
	v_readfirstlane_b32 s16, v132
	v_readfirstlane_b32 s17, v133
	s_add_u32 s16, s16, 0x2f806000
	s_addc_u32 s17, s17, 0
	s_add_i32 m0, s3, 0x12000
	s_nop 0
	global_load_lds_dwordx4 v168, s[16:17]
	v_readfirstlane_b32 s16, v134
	v_readfirstlane_b32 s17, v135
	s_lshl_b32 s3, s78, 14
	s_sub_u32 s16, s16, s3
	s_subb_u32 s17, s17, 0
	s_add_u32 s16, s16, 0x33080100
	s_addc_u32 s17, s17, 0
	s_lshl_b32 s3, s78, 10
	s_add_i32 m0, s3, 0x0
	s_nop 0
	global_load_lds_dwordx4 v167, s[16:17]
	s_add_u32 s16, s16, 0x20000
	s_addc_u32 s17, s17, 0
	s_add_i32 m0, s3, 0x2000
	s_nop 0
	global_load_lds_dwordx4 v167, s[16:17]
	ds_read_b128 v[64:67], v170 offset:32768
	ds_read_b128 v[68:71], v170 offset:40960
	ds_read_b128 v[142:145], v171 offset:32768
	ds_read_b128 v[146:149], v171 offset:40960
	ds_read_b128 v[150:153], v172 offset:32768
	s_cmp_lt_u32 s2, s27
	s_cselect_b64 vcc, -1, 0
	s_waitcnt lgkmcnt(4)
	v_mfma_f32_32x32x16_bf16 v[80:95], v[64:67], v[126:129], 0
	s_waitcnt lgkmcnt(3)
	v_mfma_f32_32x32x16_bf16 v[64:79], v[68:71], v[126:129], 0
	s_waitcnt lgkmcnt(2)
	v_mfma_f32_32x32x16_bf16 v[80:95], v[142:145], v[122:125], v[80:95]
	ds_read_b128 v[142:145], v172 offset:40960
	s_waitcnt lgkmcnt(2)
	v_mfma_f32_32x32x16_bf16 v[64:79], v[146:149], v[122:125], v[64:79]
	ds_read_b128 v[146:149], v173 offset:32768
	s_waitcnt lgkmcnt(2)
	v_mfma_f32_32x32x16_bf16 v[80:95], v[150:153], v[118:121], v[80:95]
	ds_read_b128 v[150:153], v173 offset:40960
	s_waitcnt lgkmcnt(2)
	v_mfma_f32_32x32x16_bf16 v[64:79], v[142:145], v[118:121], v[64:79]
	ds_read_b128 v[142:145], v174 offset:32768
	s_waitcnt lgkmcnt(2)
	v_mfma_f32_32x32x16_bf16 v[80:95], v[146:149], v[114:117], v[80:95]
	ds_read_b128 v[146:149], v174 offset:40960
	s_waitcnt lgkmcnt(2)
	v_mfma_f32_32x32x16_bf16 v[64:79], v[150:153], v[114:117], v[64:79]
	ds_read_b128 v[150:153], v175 offset:32768
	s_waitcnt lgkmcnt(2)
	v_mfma_f32_32x32x16_bf16 v[80:95], v[142:145], v[110:113], v[80:95]
	ds_read_b128 v[142:145], v175 offset:40960
	s_waitcnt lgkmcnt(2)
	v_mfma_f32_32x32x16_bf16 v[64:79], v[146:149], v[110:113], v[64:79]
	ds_read_b128 v[146:149], v176 offset:32768
	s_waitcnt lgkmcnt(2)
	v_mfma_f32_32x32x16_bf16 v[80:95], v[150:153], v[106:109], v[80:95]
	ds_read_b128 v[150:153], v176 offset:40960
	s_waitcnt lgkmcnt(2)
	v_mfma_f32_32x32x16_bf16 v[64:79], v[142:145], v[106:109], v[64:79]
	ds_read_b128 v[142:145], v177 offset:32768
	s_waitcnt lgkmcnt(2)
	v_mfma_f32_32x32x16_bf16 v[80:95], v[146:149], v[102:105], v[80:95]
	ds_read_b128 v[146:149], v177 offset:40960
	s_waitcnt lgkmcnt(2)
	v_mfma_f32_32x32x16_bf16 v[64:79], v[150:153], v[102:105], v[64:79]
	s_waitcnt lgkmcnt(1)
	v_mfma_f32_32x32x16_bf16 v[80:95], v[142:145], v[98:101], v[80:95]
	s_waitcnt lgkmcnt(0)
	v_mfma_f32_32x32x16_bf16 v[64:79], v[146:149], v[98:101], v[64:79]
	ds_read_b128 v[142:145], v179
	ds_read_b128 v[146:149], v179 offset:4096
	ds_read_b128 v[150:153], v163
	s_waitcnt lgkmcnt(0)
	v_mfma_f32_32x32x16_bf16 v[80:95], v[142:145], v[150:153], v[80:95]
	v_mfma_f32_32x32x16_bf16 v[64:79], v[146:149], v[150:153], v[64:79]
	ds_read_b128 v[142:145], v181
	ds_read_b128 v[146:149], v181 offset:4096
	ds_read_b128 v[150:153], v163 offset:1024
	s_waitcnt lgkmcnt(0)
	v_mfma_f32_32x32x16_bf16 v[80:95], v[142:145], v[150:153], v[80:95]
	v_mfma_f32_32x32x16_bf16 v[64:79], v[146:149], v[150:153], v[64:79]
	ds_read_b128 v[142:145], v183
	ds_read_b128 v[146:149], v183 offset:4096
	ds_read_b128 v[150:153], v163 offset:2048
	s_waitcnt lgkmcnt(0)
	v_mfma_f32_32x32x16_bf16 v[80:95], v[142:145], v[150:153], v[80:95]
	v_mfma_f32_32x32x16_bf16 v[64:79], v[146:149], v[150:153], v[64:79]
	ds_read_b128 v[142:145], v185
	ds_read_b128 v[146:149], v185 offset:4096
	ds_read_b128 v[150:153], v163 offset:3072
	s_waitcnt lgkmcnt(0)
	v_mfma_f32_32x32x16_bf16 v[80:95], v[142:145], v[150:153], v[80:95]
	v_mfma_f32_32x32x16_bf16 v[64:79], v[146:149], v[150:153], v[64:79]
	s_nop 10
	v_cndmask_b32_e32 v218, v208, v80, vcc
	v_add_f32_e32 v80, 0, v233
	v_add_f32_e32 v80, v235, v80
	v_add_f32_e32 v80, v231, v80
	v_add_f32_e32 v80, v234, v80
	v_add_f32_e32 v80, v229, v80
	v_add_f32_e32 v80, v232, v80
	v_add_f32_e32 v80, v228, v80
	v_add_f32_e32 v80, v230, v80
	v_add_f32_e32 v80, v225, v80
	v_add_f32_e32 v80, v227, v80
	v_add_f32_e32 v80, v221, v80
	v_add_f32_e32 v80, v226, v80
	v_cndmask_b32_e32 v148, v208, v64, vcc
	v_exp_f32_e32 v64, v223
	v_add_f32_e32 v80, v219, v80
	v_cndmask_b32_e32 v149, v208, v65, vcc
	v_exp_f32_e32 v65, v224
	v_add_f32_e32 v80, v222, v80
	v_cndmask_b32_e32 v146, v208, v66, vcc
	v_exp_f32_e32 v66, v236
	v_add_f32_e32 v80, v195, v80
	v_cndmask_b32_e32 v147, v208, v67, vcc
	v_exp_f32_e32 v67, v237
	v_add_f32_e32 v80, v220, v80
	v_cndmask_b32_e32 v144, v208, v68, vcc
	v_exp_f32_e32 v68, v238
	v_add_f32_e32 v80, v64, v80
	v_cndmask_b32_e32 v145, v208, v69, vcc
	v_exp_f32_e32 v69, v239
	v_add_f32_e32 v80, v65, v80
	v_cndmask_b32_e32 v142, v208, v70, vcc
	v_exp_f32_e32 v70, v240
	v_add_f32_e32 v80, v66, v80
	v_cndmask_b32_e32 v143, v208, v71, vcc
	v_exp_f32_e32 v71, v241
	v_add_f32_e32 v80, v67, v80
	v_cndmask_b32_e32 v151, v208, v94, vcc
	v_cndmask_b32_e32 v94, v208, v72, vcc
	v_exp_f32_e32 v72, v242
	v_add_f32_e32 v80, v68, v80
	v_cndmask_b32_e32 v150, v208, v95, vcc
	v_cndmask_b32_e32 v95, v208, v73, vcc
	v_exp_f32_e32 v73, v243
	v_add_f32_e32 v80, v69, v80
	v_cndmask_b32_e32 v153, v208, v92, vcc
	v_cndmask_b32_e32 v92, v208, v74, vcc
	v_exp_f32_e32 v74, v244
	v_add_f32_e32 v80, v70, v80
	v_cndmask_b32_e32 v152, v208, v93, vcc
	v_cndmask_b32_e32 v93, v208, v75, vcc
	v_exp_f32_e32 v75, v245
	v_add_f32_e32 v80, v71, v80
	v_cndmask_b32_e32 v198, v208, v90, vcc
	v_cndmask_b32_e32 v90, v208, v76, vcc
	v_exp_f32_e32 v76, v246
	v_add_f32_e32 v80, v72, v80
	v_cndmask_b32_e32 v197, v208, v91, vcc
	v_cndmask_b32_e32 v91, v208, v77, vcc
	v_exp_f32_e32 v77, v247
	v_add_f32_e32 v80, v73, v80
	v_cndmask_b32_e32 v210, v208, v88, vcc
	v_cndmask_b32_e32 v88, v208, v78, vcc
	v_exp_f32_e32 v78, v248
	v_add_f32_e32 v80, v74, v80
	v_cndmask_b32_e32 v199, v208, v89, vcc
	v_cndmask_b32_e32 v89, v208, v79, vcc
	v_exp_f32_e32 v79, v202
	v_add_f32_e32 v80, v75, v80
	v_add_f32_e32 v80, v76, v80
	v_add_f32_e32 v80, v77, v80
	v_add_f32_e32 v80, v78, v80
	v_add_f32_e32 v223, v79, v80
	v_cndmask_b32_e32 v212, v208, v86, vcc
	v_cndmask_b32_e32 v213, v208, v85, vcc
	v_cndmask_b32_e32 v214, v208, v84, vcc
	v_mov_b32_e32 v224, v223
	v_cvt_pk_bf16_f32 v84, v233, v235
	v_cvt_pk_bf16_f32 v85, v231, v234
	v_cvt_pk_bf16_f32 v86, v229, v232
	v_cndmask_b32_e32 v211, v208, v87, vcc
	v_cndmask_b32_e32 v215, v208, v83, vcc
	v_cndmask_b32_e32 v216, v208, v82, vcc
	v_cndmask_b32_e32 v217, v208, v81, vcc
	v_permlane32_swap_b32_e32 v223, v224
	v_cvt_pk_bf16_f32 v87, v228, v230
	v_permlane32_swap_b32_e32 v84, v86
	v_cvt_pk_bf16_f32 v154, v225, v227
	v_cvt_pk_bf16_f32 v155, v221, v226
	v_cvt_pk_bf16_f32 v156, v219, v222
	v_cvt_pk_bf16_f32 v157, v195, v220
	v_cvt_pk_bf16_f32 v202, v64, v65
	v_cvt_pk_bf16_f32 v203, v66, v67
	v_cvt_pk_bf16_f32 v204, v68, v69
	v_cvt_pk_bf16_f32 v205, v70, v71
	v_cvt_pk_bf16_f32 v226, v72, v73
	v_cvt_pk_bf16_f32 v227, v74, v75
	v_cvt_pk_bf16_f32 v228, v76, v77
	v_cvt_pk_bf16_f32 v229, v78, v79
	v_permlane32_swap_b32_e32 v85, v87
	v_permlane32_swap_b32_e32 v154, v156
	v_permlane32_swap_b32_e32 v155, v157
	v_permlane32_swap_b32_e32 v202, v204
	v_permlane32_swap_b32_e32 v203, v205
	v_permlane32_swap_b32_e32 v226, v228
	v_permlane32_swap_b32_e32 v227, v229
	ds_read_b64_tr_b16 v[138:139], v162 offset:0
	ds_read_b64_tr_b16 v[140:141], v162 offset:0x800
	ds_read_b64_tr_b16 v[230:231], v162 offset:0x1000
	ds_read_b64_tr_b16 v[232:233], v162 offset:0x1800
	ds_read_b64_tr_b16 v[234:235], v162 offset:0x2000
	ds_read_b64_tr_b16 v[236:237], v162 offset:0x2800
	ds_read_b64_tr_b16 v[238:239], v162 offset:0x3000
	ds_read_b64_tr_b16 v[240:241], v162 offset:0x3800
	s_waitcnt lgkmcnt(0)
	s_nop 0
	v_mfma_f32_32x32x16_bf16 v[0:15], v[84:87], v[138:141], v[0:15]
	ds_read_b64_tr_b16 v[138:139], v162 offset:0x200
	ds_read_b64_tr_b16 v[140:141], v162 offset:0xa00
	v_mfma_f32_32x32x16_bf16 v[0:15], v[154:157], v[230:233], v[0:15]
	ds_read_b64_tr_b16 v[230:231], v162 offset:0x1200
	ds_read_b64_tr_b16 v[232:233], v162 offset:0x1a00
	v_mfma_f32_32x32x16_bf16 v[0:15], v[202:205], v[234:237], v[0:15]
	ds_read_b64_tr_b16 v[234:235], v162 offset:0x2200
	ds_read_b64_tr_b16 v[236:237], v162 offset:0x2a00
	v_mfma_f32_32x32x16_bf16 v[0:15], v[226:229], v[238:241], v[0:15]
	ds_read_b64_tr_b16 v[238:239], v162 offset:0x3200
	ds_read_b64_tr_b16 v[240:241], v162 offset:0x3a00
	s_waitcnt lgkmcnt(0)
	v_mfma_f32_32x32x16_bf16 v[48:63], v[84:87], v[138:141], v[48:63]
	ds_read_b64_tr_b16 v[138:139], v162 offset:0x400
	ds_read_b64_tr_b16 v[140:141], v162 offset:0xc00
	v_mfma_f32_32x32x16_bf16 v[48:63], v[154:157], v[230:233], v[48:63]
	ds_read_b64_tr_b16 v[230:231], v162 offset:0x1400
	ds_read_b64_tr_b16 v[232:233], v162 offset:0x1c00
	v_mfma_f32_32x32x16_bf16 v[48:63], v[202:205], v[234:237], v[48:63]
	ds_read_b64_tr_b16 v[234:235], v162 offset:0x2400
	ds_read_b64_tr_b16 v[236:237], v162 offset:0x2c00
	v_mfma_f32_32x32x16_bf16 v[48:63], v[226:229], v[238:241], v[48:63]
	ds_read_b64_tr_b16 v[238:239], v162 offset:0x3400
	ds_read_b64_tr_b16 v[240:241], v162 offset:0x3c00
	s_waitcnt lgkmcnt(0)
	v_mfma_f32_32x32x16_bf16 v[32:47], v[84:87], v[138:141], v[32:47]
	ds_read_b64_tr_b16 v[138:139], v162 offset:0x600
	ds_read_b64_tr_b16 v[140:141], v162 offset:0xe00
	v_mfma_f32_32x32x16_bf16 v[32:47], v[154:157], v[230:233], v[32:47]
	ds_read_b64_tr_b16 v[230:231], v162 offset:0x1600
	ds_read_b64_tr_b16 v[232:233], v162 offset:0x1e00
	v_mfma_f32_32x32x16_bf16 v[32:47], v[202:205], v[234:237], v[32:47]
	ds_read_b64_tr_b16 v[234:235], v162 offset:0x2600
	ds_read_b64_tr_b16 v[236:237], v162 offset:0x2e00
	v_mfma_f32_32x32x16_bf16 v[32:47], v[226:229], v[238:241], v[32:47]
	ds_read_b64_tr_b16 v[238:239], v162 offset:0x3600
	ds_read_b64_tr_b16 v[240:241], v162 offset:0x3e00
	s_waitcnt lgkmcnt(0)
	v_mfma_f32_32x32x16_bf16 v[16:31], v[84:87], v[138:141], v[16:31]
	v_max_f32_e32 v84, v217, v217
	v_max_f32_e32 v85, v218, v218
	v_max_f32_e32 v84, v85, v84
	v_max3_f32 v84, v84, v216, v215
	v_max3_f32 v84, v84, v214, v213
	v_max3_f32 v84, v84, v212, v211
	v_max3_f32 v84, v84, v210, v199
	v_mfma_f32_32x32x16_bf16 v[16:31], v[154:157], v[230:233], v[16:31]
	v_max3_f32 v84, v84, v198, v197
	v_max3_f32 v84, v84, v153, v152
	v_max3_f32 v84, v84, v151, v150
	v_max3_f32 v84, v84, v148, v149
	v_max3_f32 v84, v84, v146, v147
	v_max3_f32 v84, v84, v144, v145
	v_max3_f32 v84, v84, v142, v143
	v_mfma_f32_32x32x16_bf16 v[16:31], v[202:205], v[234:237], v[16:31]
	v_max3_f32 v84, v84, v94, v95
	v_max3_f32 v84, v84, v92, v93
	v_max3_f32 v84, v84, v90, v91
	v_max3_f32 v84, v84, v88, v89
	v_mov_b32_e32 v85, v84
	s_nop 1
	v_permlane32_swap_b32_e32 v84, v85
	v_mfma_f32_32x32x16_bf16 v[16:31], v[226:229], v[238:241], v[16:31]
	v_max_f32_e32 v85, v85, v85
	v_max_f32_e32 v84, v84, v84
	v_max_f32_e32 v84, v84, v85
	v_sub_f32_e32 v85, v84, v165
	v_cmp_ge_f32_e32 vcc, s21, v85
	v_mov_b32_e32 v195, 1.0
	s_cmp_eq_u64 vcc, exec
	s_cbranch_scc0 .LBB0_751
.LBB0_744:
	v_cmp_gt_f32_e32 vcc, 1.0, v195
	s_cbranch_vccz .LBB0_748
	s_and_saveexec_b64 s[16:17], s[38:39]
	ds_write_b32 v160, v195 offset:128
	s_or_b64 exec, exec, s[16:17]
	s_waitcnt lgkmcnt(0)
	v_add_u32_e32 v76, s19, v130
	ds_read_b128 v[64:67], v76 offset:224
	ds_read_b128 v[68:71], v76 offset:192
	ds_read_b128 v[72:75], v76 offset:160
	ds_read_b128 v[76:79], v76 offset:128
	s_waitcnt lgkmcnt(3)
	v_pk_mul_f32 v[12:13], v[12:13], v[64:65]
	s_waitcnt lgkmcnt(2)
	v_pk_mul_f32 v[8:9], v[8:9], v[68:69]
	s_waitcnt lgkmcnt(1)
	v_pk_mul_f32 v[4:5], v[4:5], v[72:73]
	v_pk_mul_f32 v[14:15], v[14:15], v[66:67]
	v_pk_mul_f32 v[10:11], v[10:11], v[70:71]
	v_pk_mul_f32 v[6:7], v[6:7], v[74:75]
	s_waitcnt lgkmcnt(0)
	v_pk_mul_f32 v[2:3], v[2:3], v[78:79]
	v_pk_mul_f32 v[0:1], v[0:1], v[76:77]
	v_pk_mul_f32 v[60:61], v[60:61], v[64:65]
	v_pk_mul_f32 v[56:57], v[56:57], v[68:69]
	v_pk_mul_f32 v[52:53], v[52:53], v[72:73]
	v_pk_mul_f32 v[62:63], v[62:63], v[66:67]
	v_pk_mul_f32 v[58:59], v[58:59], v[70:71]
	v_pk_mul_f32 v[54:55], v[54:55], v[74:75]
	v_pk_mul_f32 v[50:51], v[50:51], v[78:79]
	v_pk_mul_f32 v[48:49], v[48:49], v[76:77]
	v_pk_mul_f32 v[44:45], v[44:45], v[64:65]
	v_pk_mul_f32 v[40:41], v[40:41], v[68:69]
	v_pk_mul_f32 v[36:37], v[36:37], v[72:73]
	v_pk_mul_f32 v[46:47], v[46:47], v[66:67]
	v_pk_mul_f32 v[42:43], v[42:43], v[70:71]
	v_pk_mul_f32 v[38:39], v[38:39], v[74:75]
	v_pk_mul_f32 v[34:35], v[34:35], v[78:79]
	v_pk_mul_f32 v[32:33], v[32:33], v[76:77]
	v_pk_mul_f32 v[28:29], v[28:29], v[64:65]
	v_pk_mul_f32 v[24:25], v[24:25], v[68:69]
	v_pk_mul_f32 v[20:21], v[20:21], v[72:73]
	v_pk_mul_f32 v[30:31], v[30:31], v[66:67]
	v_pk_mul_f32 v[26:27], v[26:27], v[70:71]
	v_pk_mul_f32 v[22:23], v[22:23], v[74:75]
	v_pk_mul_f32 v[18:19], v[18:19], v[78:79]
	v_pk_mul_f32 v[16:17], v[16:17], v[76:77]
.LBB0_748:
	v_fmamk_f32 v64, v218, 0x3dd53b94, v136
	v_fmamk_f32 v65, v217, 0x3dd53b94, v136
	v_fmamk_f32 v66, v216, 0x3dd53b94, v136
	v_fmamk_f32 v67, v215, 0x3dd53b94, v136
	v_fmamk_f32 v68, v214, 0x3dd53b94, v136
	v_fmamk_f32 v69, v213, 0x3dd53b94, v136
	v_fmamk_f32 v70, v212, 0x3dd53b94, v136
	v_fmamk_f32 v71, v211, 0x3dd53b94, v136
	v_fmamk_f32 v72, v210, 0x3dd53b94, v136
	v_fmamk_f32 v73, v199, 0x3dd53b94, v136
	v_fmamk_f32 v74, v198, 0x3dd53b94, v136
	v_fmamk_f32 v75, v197, 0x3dd53b94, v136
	v_fmamk_f32 v76, v153, 0x3dd53b94, v136
	v_fmamk_f32 v77, v152, 0x3dd53b94, v136
	v_fmamk_f32 v78, v151, 0x3dd53b94, v136
	v_fmamk_f32 v79, v150, 0x3dd53b94, v136
	v_exp_f32_e32 v220, v64
	v_exp_f32_e32 v222, v65
	v_exp_f32_e32 v218, v66
	v_exp_f32_e32 v221, v67
	v_exp_f32_e32 v216, v68
	v_exp_f32_e32 v219, v69
	v_exp_f32_e32 v215, v70
	v_exp_f32_e32 v217, v71
	v_exp_f32_e32 v212, v72
	v_exp_f32_e32 v214, v73
	v_exp_f32_e32 v210, v74
	v_exp_f32_e32 v213, v75
	v_exp_f32_e32 v198, v76
	v_exp_f32_e32 v211, v77
	v_exp_f32_e32 v197, v78
	v_exp_f32_e32 v199, v79
	v_add_f32_e32 v64, v193, v194
	v_fmac_f32_e32 v64, v186, v161
	v_add_f32_e32 v161, v223, v224
	s_add_i32 s26, s26, 2
	v_pk_fma_f32 v[148:149], v[148:149], s[74:75], v[136:137] op_sel_hi:[1,0,0]
	v_pk_fma_f32 v[146:147], v[146:147], s[74:75], v[136:137] op_sel_hi:[1,0,0]
	v_pk_fma_f32 v[144:145], v[144:145], s[74:75], v[136:137] op_sel_hi:[1,0,0]
	v_pk_fma_f32 v[140:141], v[142:143], s[74:75], v[136:137] op_sel_hi:[1,0,0]
	v_pk_fma_f32 v[138:139], v[94:95], s[74:75], v[136:137] op_sel_hi:[1,0,0]
	v_pk_fma_f32 v[152:153], v[92:93], s[74:75], v[136:137] op_sel_hi:[1,0,0]
	v_pk_fma_f32 v[150:151], v[90:91], s[74:75], v[136:137] op_sel_hi:[1,0,0]
	v_pk_fma_f32 v[142:143], v[88:89], s[74:75], v[136:137] op_sel_hi:[1,0,0]
	v_fmac_f32_e32 v161, v64, v196
	v_lshl_add_u64 v[132:133], v[132:133], 0, s[72:73]
	s_cmp_ge_u32 s26, s10
	v_lshl_add_u64 v[134:135], v[134:135], 0, s[66:67]
	s_waitcnt vmcnt(0) lgkmcnt(0)
	s_barrier
	s_cbranch_scc1 .LBB0_752
	v_mov_b32_e32 v186, v195
	s_branch .LBB0_738

.Latt1_738:
	v_readfirstlane_b32 s16, v134
	v_readfirstlane_b32 s17, v135
	s_lshl_b32 s3, s78, 10
	s_add_u32 s16, s16, 0x33080000
	s_addc_u32 s17, s17, 0
	s_add_i32 m0, s3, 0x8000
	s_nop 0
	global_load_lds_dwordx4 v166, s[16:17]
	s_add_u32 s16, s16, 0x20000
	s_addc_u32 s17, s17, 0
	s_add_i32 m0, s3, 0xa000
	s_nop 0
	global_load_lds_dwordx4 v166, s[16:17]
	v_readfirstlane_b32 s16, v132
	v_readfirstlane_b32 s17, v133
	s_add_u32 s16, s16, 0x2f804000
	s_addc_u32 s17, s17, 0
	s_add_i32 m0, s3, 0x10000
	s_nop 0
	global_load_lds_dwordx4 v168, s[16:17]
	v_readfirstlane_b32 s16, v134
	v_readfirstlane_b32 s17, v135
	s_lshl_b32 s3, s78, 14
	s_sub_u32 s16, s16, s3
	s_subb_u32 s17, s17, 0
	s_add_u32 s16, s16, 0x33040100
	s_addc_u32 s17, s17, 0
	s_lshl_b32 s3, s78, 10
	s_add_i32 m0, s3, 0x4000
	s_nop 0
	global_load_lds_dwordx4 v167, s[16:17]
	s_add_u32 s16, s16, 0x20000
	s_addc_u32 s17, s17, 0
	s_add_i32 m0, s3, 0x6000
	s_nop 0
	global_load_lds_dwordx4 v167, s[16:17]
	v_add_f32_e32 v80, 0, v220
	v_add_f32_e32 v80, v222, v80
	v_add_f32_e32 v80, v218, v80
	v_add_f32_e32 v80, v221, v80
	v_add_f32_e32 v80, v216, v80
	v_add_f32_e32 v80, v219, v80
	v_add_f32_e32 v80, v215, v80
	v_add_f32_e32 v80, v217, v80
	v_add_f32_e32 v80, v212, v80
	v_add_f32_e32 v80, v214, v80
	v_add_f32_e32 v80, v210, v80
	v_add_f32_e32 v80, v213, v80
	v_exp_f32_e32 v64, v148
	v_add_f32_e32 v80, v198, v80
	v_exp_f32_e32 v65, v149
	v_add_f32_e32 v80, v211, v80
	v_exp_f32_e32 v66, v146
	v_add_f32_e32 v80, v197, v80
	v_exp_f32_e32 v67, v147
	v_add_f32_e32 v80, v199, v80
	v_exp_f32_e32 v68, v144
	v_add_f32_e32 v80, v64, v80
	v_exp_f32_e32 v69, v145
	v_add_f32_e32 v80, v65, v80
	v_exp_f32_e32 v70, v140
	v_add_f32_e32 v80, v66, v80
	v_exp_f32_e32 v71, v141
	v_add_f32_e32 v80, v67, v80
	v_exp_f32_e32 v72, v138
	v_add_f32_e32 v80, v68, v80
	v_exp_f32_e32 v73, v139
	v_add_f32_e32 v80, v69, v80
	v_exp_f32_e32 v74, v152
	v_add_f32_e32 v80, v70, v80
	v_exp_f32_e32 v75, v153
	v_add_f32_e32 v80, v71, v80
	v_exp_f32_e32 v76, v150
	v_add_f32_e32 v80, v72, v80
	v_exp_f32_e32 v77, v151
	v_add_f32_e32 v80, v73, v80
	v_exp_f32_e32 v78, v142
	v_add_f32_e32 v80, v74, v80
	v_exp_f32_e32 v79, v143
	v_add_f32_e32 v80, v75, v80
	v_add_f32_e32 v80, v76, v80
	v_add_f32_e32 v80, v77, v80
	v_add_f32_e32 v80, v78, v80
	v_add_f32_e32 v246, v79, v80
	v_cvt_pk_bf16_f32 v142, v212, v214
	v_cvt_pk_bf16_f32 v143, v210, v213
	v_cvt_pk_bf16_f32 v144, v198, v211
	v_cvt_pk_bf16_f32 v145, v197, v199
	v_cvt_pk_bf16_f32 v146, v64, v65
	v_cvt_pk_bf16_f32 v147, v66, v67
	v_cvt_pk_bf16_f32 v148, v68, v69
	v_cvt_pk_bf16_f32 v149, v70, v71
	v_cvt_pk_bf16_f32 v150, v72, v73
	v_cvt_pk_bf16_f32 v151, v74, v75
	v_cvt_pk_bf16_f32 v152, v76, v77
	v_cvt_pk_bf16_f32 v153, v78, v79
	v_permlane32_swap_b32_e32 v142, v144
	v_permlane32_swap_b32_e32 v143, v145
	v_permlane32_swap_b32_e32 v146, v148
	v_permlane32_swap_b32_e32 v147, v149
	v_permlane32_swap_b32_e32 v150, v152
	v_permlane32_swap_b32_e32 v151, v153
	s_add_i32 s2, s26, -1
	ds_read_b128 v[64:67], v170 offset:49152
	ds_read_b128 v[68:71], v170 offset:57344
	ds_read_b128 v[154:157], v171 offset:49152
	ds_read_b128 v[190:193], v171 offset:57344
	ds_read_b128 v[202:205], v172 offset:49152
	ds_read_b128 v[224:227], v172 offset:57344
	s_add_i32 s3, 0, 0x12000
	v_add_u32_e32 v189, s3, v178
	s_cmp_gt_u32 s2, s27
	s_cselect_b64 vcc, -1, 0
	s_waitcnt lgkmcnt(5)
	v_mfma_f32_32x32x16_bf16 v[80:95], v[64:67], v[126:129], 0
	s_waitcnt lgkmcnt(4)
	v_mfma_f32_32x32x16_bf16 v[64:79], v[68:71], v[126:129], 0
	s_waitcnt lgkmcnt(3)
	v_mfma_f32_32x32x16_bf16 v[80:95], v[154:157], v[122:125], v[80:95]
	ds_read_b128 v[154:157], v173 offset:49152
	s_waitcnt lgkmcnt(3)
	v_mfma_f32_32x32x16_bf16 v[64:79], v[190:193], v[122:125], v[64:79]
	ds_read_b128 v[190:193], v173 offset:57344
	s_waitcnt lgkmcnt(3)
	v_mfma_f32_32x32x16_bf16 v[80:95], v[202:205], v[118:121], v[80:95]
	ds_read_b128 v[202:205], v174 offset:49152
	s_waitcnt lgkmcnt(3)
	v_mfma_f32_32x32x16_bf16 v[64:79], v[224:227], v[118:121], v[64:79]
	ds_read_b128 v[224:227], v174 offset:57344
	s_waitcnt lgkmcnt(3)
	v_mfma_f32_32x32x16_bf16 v[80:95], v[154:157], v[114:117], v[80:95]
	ds_read_b128 v[154:157], v175 offset:49152
	s_waitcnt lgkmcnt(3)
	v_mfma_f32_32x32x16_bf16 v[64:79], v[190:193], v[114:117], v[64:79]
	ds_read_b128 v[190:193], v175 offset:57344
	s_waitcnt lgkmcnt(3)
	v_mfma_f32_32x32x16_bf16 v[80:95], v[202:205], v[110:113], v[80:95]
	ds_read_b128 v[202:205], v176 offset:49152
	s_waitcnt lgkmcnt(3)
	v_mfma_f32_32x32x16_bf16 v[64:79], v[224:227], v[110:113], v[64:79]
	ds_read_b128 v[224:227], v176 offset:57344
	s_waitcnt lgkmcnt(3)
	v_mfma_f32_32x32x16_bf16 v[80:95], v[154:157], v[106:109], v[80:95]
	ds_read_b128 v[154:157], v177 offset:49152
	s_waitcnt lgkmcnt(3)
	v_mfma_f32_32x32x16_bf16 v[64:79], v[190:193], v[106:109], v[64:79]
	ds_read_b128 v[190:193], v177 offset:57344
	s_waitcnt lgkmcnt(3)
	v_mfma_f32_32x32x16_bf16 v[80:95], v[202:205], v[102:105], v[80:95]
	s_waitcnt lgkmcnt(2)
	v_mfma_f32_32x32x16_bf16 v[64:79], v[224:227], v[102:105], v[64:79]
	s_waitcnt lgkmcnt(1)
	v_mfma_f32_32x32x16_bf16 v[80:95], v[154:157], v[98:101], v[80:95]
	s_waitcnt lgkmcnt(0)
	v_mfma_f32_32x32x16_bf16 v[64:79], v[190:193], v[98:101], v[64:79]
	ds_read_b128 v[154:157], v189
	ds_read_b128 v[190:193], v189 offset:4096
	ds_read_b128 v[202:205], v163
	s_waitcnt lgkmcnt(0)
	v_mfma_f32_32x32x16_bf16 v[80:95], v[154:157], v[202:205], v[80:95]
	v_mfma_f32_32x32x16_bf16 v[64:79], v[190:193], v[202:205], v[64:79]
	v_add_u32_e32 v190, s3, v180
	ds_read_b128 v[154:157], v190
	ds_read_b128 v[192:195], v190 offset:4096
	ds_read_b128 v[202:205], v163 offset:1024
	v_add_u32_e32 v191, s3, v182
	s_waitcnt lgkmcnt(0)
	v_mfma_f32_32x32x16_bf16 v[80:95], v[154:157], v[202:205], v[80:95]
	v_mfma_f32_32x32x16_bf16 v[64:79], v[192:195], v[202:205], v[64:79]
	ds_read_b128 v[154:157], v191
	ds_read_b128 v[192:195], v191 offset:4096
	ds_read_b128 v[202:205], v163 offset:2048
	s_waitcnt lgkmcnt(0)
	v_mfma_f32_32x32x16_bf16 v[80:95], v[154:157], v[202:205], v[80:95]
	v_mfma_f32_32x32x16_bf16 v[64:79], v[192:195], v[202:205], v[64:79]
	v_add_u32_e32 v192, s3, v184
	ds_read_b128 v[154:157], v192
	ds_read_b128 v[202:205], v192 offset:4096
	ds_read_b128 v[224:227], v163 offset:3072
	s_waitcnt lgkmcnt(0)
	v_mfma_f32_32x32x16_bf16 v[80:95], v[154:157], v[224:227], v[80:95]
	v_mfma_f32_32x32x16_bf16 v[64:79], v[202:205], v[224:227], v[64:79]
	s_nop 10
	v_cndmask_b32_e32 v240, v80, v208, vcc
	v_cndmask_b32_e32 v244, v64, v208, vcc
	v_cndmask_b32_e32 v245, v65, v208, vcc
	v_cndmask_b32_e32 v242, v66, v208, vcc
	v_cndmask_b32_e32 v243, v67, v208, vcc
	v_cndmask_b32_e32 v238, v68, v208, vcc
	v_cndmask_b32_e32 v239, v69, v208, vcc
	v_cndmask_b32_e32 v234, v70, v208, vcc
	v_cndmask_b32_e32 v235, v71, v208, vcc
	v_cndmask_b32_e32 v230, v72, v208, vcc
	v_cndmask_b32_e32 v231, v73, v208, vcc
	v_cndmask_b32_e32 v227, v74, v208, vcc
	v_cndmask_b32_e32 v228, v75, v208, vcc
	v_cndmask_b32_e32 v225, v76, v208, vcc
	v_cndmask_b32_e32 v195, v90, v208, vcc
	v_cndmask_b32_e32 v90, v77, v208, vcc
	v_cndmask_b32_e32 v223, v88, v208, vcc
	v_cndmask_b32_e32 v88, v78, v208, vcc
	v_cndmask_b32_e32 v224, v89, v208, vcc
	v_cndmask_b32_e32 v89, v79, v208, vcc
	v_cndmask_b32_e32 v226, v86, v208, vcc
	v_cndmask_b32_e32 v232, v84, v208, vcc
	v_cndmask_b32_e32 v233, v85, v208, vcc
	v_cndmask_b32_e32 v94, v94, v208, vcc
	v_cndmask_b32_e32 v95, v95, v208, vcc
	v_cndmask_b32_e32 v92, v92, v208, vcc
	v_cndmask_b32_e32 v93, v93, v208, vcc
	v_cndmask_b32_e32 v91, v91, v208, vcc
	v_cndmask_b32_e32 v229, v87, v208, vcc
	v_cndmask_b32_e32 v236, v82, v208, vcc
	v_cndmask_b32_e32 v237, v83, v208, vcc
	v_cndmask_b32_e32 v241, v81, v208, vcc
	v_mov_b32_e32 v193, v246
	v_mov_b32_e32 v194, v246
	v_cvt_pk_bf16_f32 v84, v220, v222
	v_cvt_pk_bf16_f32 v85, v218, v221
	v_cvt_pk_bf16_f32 v86, v216, v219
	v_cvt_pk_bf16_f32 v87, v215, v217
	s_nop 1
	v_permlane32_swap_b32_e32 v193, v194
	v_permlane32_swap_b32_e32 v84, v86
	v_permlane32_swap_b32_e32 v85, v87
	ds_read_b64_tr_b16 v[154:155], v164 offset:0
	ds_read_b64_tr_b16 v[156:157], v164 offset:0x800
	ds_read_b64_tr_b16 v[196:197], v164 offset:0x1000
	ds_read_b64_tr_b16 v[198:199], v164 offset:0x1800
	ds_read_b64_tr_b16 v[202:203], v164 offset:0x2000
	ds_read_b64_tr_b16 v[204:205], v164 offset:0x2800
	ds_read_b64_tr_b16 v[210:211], v164 offset:0x3000
	ds_read_b64_tr_b16 v[212:213], v164 offset:0x3800
	s_waitcnt lgkmcnt(0)
	s_nop 0
	v_mfma_f32_32x32x16_bf16 v[0:15], v[84:87], v[154:157], v[0:15]
	ds_read_b64_tr_b16 v[154:155], v164 offset:0x200
	ds_read_b64_tr_b16 v[156:157], v164 offset:0xa00
	v_mfma_f32_32x32x16_bf16 v[0:15], v[142:145], v[196:199], v[0:15]
	ds_read_b64_tr_b16 v[196:197], v164 offset:0x1200
	ds_read_b64_tr_b16 v[198:199], v164 offset:0x1a00
	v_mfma_f32_32x32x16_bf16 v[0:15], v[146:149], v[202:205], v[0:15]
	ds_read_b64_tr_b16 v[202:203], v164 offset:0x2200
	ds_read_b64_tr_b16 v[204:205], v164 offset:0x2a00
	v_mfma_f32_32x32x16_bf16 v[0:15], v[150:153], v[210:213], v[0:15]
	ds_read_b64_tr_b16 v[210:211], v164 offset:0x3200
	ds_read_b64_tr_b16 v[212:213], v164 offset:0x3a00
	s_waitcnt lgkmcnt(0)
	v_mfma_f32_32x32x16_bf16 v[48:63], v[84:87], v[154:157], v[48:63]
	ds_read_b64_tr_b16 v[154:155], v164 offset:0x400
	ds_read_b64_tr_b16 v[156:157], v164 offset:0xc00
	v_mfma_f32_32x32x16_bf16 v[48:63], v[142:145], v[196:199], v[48:63]
	ds_read_b64_tr_b16 v[196:197], v164 offset:0x1400
	ds_read_b64_tr_b16 v[198:199], v164 offset:0x1c00
	v_mfma_f32_32x32x16_bf16 v[48:63], v[146:149], v[202:205], v[48:63]
	ds_read_b64_tr_b16 v[202:203], v164 offset:0x2400
	ds_read_b64_tr_b16 v[204:205], v164 offset:0x2c00
	v_mfma_f32_32x32x16_bf16 v[48:63], v[150:153], v[210:213], v[48:63]
	ds_read_b64_tr_b16 v[210:211], v164 offset:0x3400
	ds_read_b64_tr_b16 v[212:213], v164 offset:0x3c00
	s_waitcnt lgkmcnt(0)
	v_mfma_f32_32x32x16_bf16 v[32:47], v[84:87], v[154:157], v[32:47]
	ds_read_b64_tr_b16 v[154:155], v164 offset:0x600
	ds_read_b64_tr_b16 v[156:157], v164 offset:0xe00
	v_mfma_f32_32x32x16_bf16 v[32:47], v[142:145], v[196:199], v[32:47]
	ds_read_b64_tr_b16 v[196:197], v164 offset:0x1600
	ds_read_b64_tr_b16 v[198:199], v164 offset:0x1e00
	v_mfma_f32_32x32x16_bf16 v[32:47], v[146:149], v[202:205], v[32:47]
	ds_read_b64_tr_b16 v[202:203], v164 offset:0x2600
	ds_read_b64_tr_b16 v[204:205], v164 offset:0x2e00
	v_mfma_f32_32x32x16_bf16 v[32:47], v[150:153], v[210:213], v[32:47]
	ds_read_b64_tr_b16 v[210:211], v164 offset:0x3600
	ds_read_b64_tr_b16 v[212:213], v164 offset:0x3e00
	s_waitcnt lgkmcnt(0)
	v_mfma_f32_32x32x16_bf16 v[16:31], v[84:87], v[154:157], v[16:31]
	v_max_f32_e32 v84, v241, v241
	v_max_f32_e32 v85, v240, v240
	v_max_f32_e32 v84, v85, v84
	v_max3_f32 v84, v84, v236, v237
	v_max3_f32 v84, v84, v232, v233
	v_max3_f32 v84, v84, v226, v229
	v_max3_f32 v84, v84, v223, v224
	v_mfma_f32_32x32x16_bf16 v[16:31], v[142:145], v[196:199], v[16:31]
	v_max3_f32 v84, v84, v195, v91
	v_max3_f32 v84, v84, v92, v93
	v_max3_f32 v84, v84, v94, v95
	v_max3_f32 v84, v84, v244, v245
	v_max3_f32 v84, v84, v242, v243
	v_max3_f32 v84, v84, v238, v239
	v_max3_f32 v84, v84, v234, v235
	v_mfma_f32_32x32x16_bf16 v[16:31], v[146:149], v[202:205], v[16:31]
	v_max3_f32 v84, v84, v230, v231
	v_max3_f32 v84, v84, v227, v228
	v_max3_f32 v84, v84, v225, v90
	v_max3_f32 v84, v84, v88, v89
	v_mov_b32_e32 v85, v84
	s_nop 1
	v_permlane32_swap_b32_e32 v84, v85
	v_mfma_f32_32x32x16_bf16 v[16:31], v[150:153], v[210:213], v[16:31]
	v_max_f32_e32 v85, v85, v85
	v_max_f32_e32 v84, v84, v84
	v_max_f32_e32 v84, v84, v85
	v_sub_f32_e32 v85, v84, v165
	v_cmp_ge_f32_e32 vcc, s21, v85
	v_mov_b32_e32 v196, 1.0
	s_cmp_eq_u64 vcc, exec
	s_cbranch_scc0 .Latt1_750

.Latt1_743:
	v_mul_f32_e32 v136, 0xbdd53b94, v165
	v_fmamk_f32 v78, v94, 0x3dd53b94, v136
	v_fmamk_f32 v74, v195, 0x3dd53b94, v136
	v_exp_f32_e32 v195, v78
	v_fmamk_f32 v64, v240, 0x3dd53b94, v136
	v_fmamk_f32 v65, v241, 0x3dd53b94, v136
	v_fmamk_f32 v66, v236, 0x3dd53b94, v136
	v_fmamk_f32 v67, v237, 0x3dd53b94, v136
	v_fmamk_f32 v68, v232, 0x3dd53b94, v136
	v_fmamk_f32 v69, v233, 0x3dd53b94, v136
	v_fmamk_f32 v70, v226, 0x3dd53b94, v136
	v_fmamk_f32 v71, v229, 0x3dd53b94, v136
	v_fmamk_f32 v72, v223, 0x3dd53b94, v136
	v_fmamk_f32 v73, v224, 0x3dd53b94, v136
	v_fmamk_f32 v75, v91, 0x3dd53b94, v136
	v_fmamk_f32 v76, v92, 0x3dd53b94, v136
	v_fmamk_f32 v77, v93, 0x3dd53b94, v136
	v_fmamk_f32 v79, v95, 0x3dd53b94, v136
	v_fmamk_f32 v223, v244, 0x3dd53b94, v136
	v_fmamk_f32 v224, v245, 0x3dd53b94, v136
	v_fmamk_f32 v236, v242, 0x3dd53b94, v136
	v_fmamk_f32 v237, v243, 0x3dd53b94, v136
	v_fmamk_f32 v238, v238, 0x3dd53b94, v136
	v_fmamk_f32 v239, v239, 0x3dd53b94, v136
	v_fmamk_f32 v240, v234, 0x3dd53b94, v136
	v_fmamk_f32 v241, v235, 0x3dd53b94, v136
	v_fmamk_f32 v242, v230, 0x3dd53b94, v136
	v_fmamk_f32 v243, v231, 0x3dd53b94, v136
	v_fmamk_f32 v244, v227, 0x3dd53b94, v136
	v_fmamk_f32 v245, v228, 0x3dd53b94, v136
	v_fmamk_f32 v246, v225, 0x3dd53b94, v136
	v_exp_f32_e32 v233, v64
	v_exp_f32_e32 v235, v65
	v_exp_f32_e32 v231, v66
	v_exp_f32_e32 v234, v67
	v_exp_f32_e32 v229, v68
	v_exp_f32_e32 v232, v69
	v_exp_f32_e32 v228, v70
	v_exp_f32_e32 v230, v71
	v_exp_f32_e32 v225, v72
	v_exp_f32_e32 v227, v73
	v_exp_f32_e32 v221, v74
	v_exp_f32_e32 v226, v75
	v_exp_f32_e32 v219, v76
	v_exp_f32_e32 v222, v77
	v_exp_f32_e32 v220, v79
	v_fmamk_f32 v247, v90, 0x3dd53b94, v136
	v_fmamk_f32 v248, v88, 0x3dd53b94, v136
	v_fmamk_f32 v202, v89, 0x3dd53b94, v136
	s_waitcnt vmcnt(0) lgkmcnt(0)
	s_barrier
	v_readfirstlane_b32 s16, v134
	v_readfirstlane_b32 s17, v135
	s_lshl_b32 s3, s78, 10
	s_add_u32 s16, s16, 0x330c0000
	s_addc_u32 s17, s17, 0
	s_add_i32 m0, s3, 0xc000
	s_nop 0
	global_load_lds_dwordx4 v166, s[16:17]
	s_add_u32 s16, s16, 0x20000
	s_addc_u32 s17, s17, 0
	s_add_i32 m0, s3, 0xe000
	s_nop 0
	global_load_lds_dwordx4 v166, s[16:17]
	v_readfirstlane_b32 s16, v132
	v_readfirstlane_b32 s17, v133
	s_add_u32 s16, s16, 0x2f806000
	s_addc_u32 s17, s17, 0
	s_add_i32 m0, s3, 0x12000
	s_nop 0
	global_load_lds_dwordx4 v168, s[16:17]
	v_readfirstlane_b32 s16, v134
	v_readfirstlane_b32 s17, v135
	s_lshl_b32 s3, s78, 14
	s_sub_u32 s16, s16, s3
	s_subb_u32 s17, s17, 0
	s_add_u32 s16, s16, 0x33080100
	s_addc_u32 s17, s17, 0
	s_lshl_b32 s3, s78, 10
	s_add_i32 m0, s3, 0x0
	s_nop 0
	global_load_lds_dwordx4 v167, s[16:17]
	s_add_u32 s16, s16, 0x20000
	s_addc_u32 s17, s17, 0
	s_add_i32 m0, s3, 0x2000
	s_nop 0
	global_load_lds_dwordx4 v167, s[16:17]
	v_add_f32_e32 v80, 0, v233
	v_add_f32_e32 v80, v235, v80
	v_add_f32_e32 v80, v231, v80
	v_add_f32_e32 v80, v234, v80
	v_add_f32_e32 v80, v229, v80
	v_add_f32_e32 v80, v232, v80
	v_add_f32_e32 v80, v228, v80
	v_add_f32_e32 v80, v230, v80
	v_add_f32_e32 v80, v225, v80
	v_add_f32_e32 v80, v227, v80
	v_add_f32_e32 v80, v221, v80
	v_add_f32_e32 v80, v226, v80
	v_exp_f32_e32 v64, v223
	v_add_f32_e32 v80, v219, v80
	v_exp_f32_e32 v65, v224
	v_add_f32_e32 v80, v222, v80
	v_exp_f32_e32 v66, v236
	v_add_f32_e32 v80, v195, v80
	v_exp_f32_e32 v67, v237
	v_add_f32_e32 v80, v220, v80
	v_exp_f32_e32 v68, v238
	v_add_f32_e32 v80, v64, v80
	v_exp_f32_e32 v69, v239
	v_add_f32_e32 v80, v65, v80
	v_exp_f32_e32 v70, v240
	v_add_f32_e32 v80, v66, v80
	v_exp_f32_e32 v71, v241
	v_add_f32_e32 v80, v67, v80
	v_exp_f32_e32 v72, v242
	v_add_f32_e32 v80, v68, v80
	v_exp_f32_e32 v73, v243
	v_add_f32_e32 v80, v69, v80
	v_exp_f32_e32 v74, v244
	v_add_f32_e32 v80, v70, v80
	v_exp_f32_e32 v75, v245
	v_add_f32_e32 v80, v71, v80
	v_exp_f32_e32 v76, v246
	v_add_f32_e32 v80, v72, v80
	v_exp_f32_e32 v77, v247
	v_add_f32_e32 v80, v73, v80
	v_exp_f32_e32 v78, v248
	v_add_f32_e32 v80, v74, v80
	v_exp_f32_e32 v79, v202
	v_add_f32_e32 v80, v75, v80
	v_add_f32_e32 v80, v76, v80
	v_add_f32_e32 v80, v77, v80
	v_add_f32_e32 v80, v78, v80
	v_add_f32_e32 v223, v79, v80
	v_mov_b32_e32 v224, v223
	v_cvt_pk_bf16_f32 v247, v229, v232
	v_cvt_pk_bf16_f32 v248, v228, v230
	v_cvt_pk_bf16_f32 v154, v225, v227
	v_cvt_pk_bf16_f32 v155, v221, v226
	v_cvt_pk_bf16_f32 v156, v219, v222
	v_cvt_pk_bf16_f32 v157, v195, v220
	v_cvt_pk_bf16_f32 v202, v64, v65
	v_cvt_pk_bf16_f32 v203, v66, v67
	v_cvt_pk_bf16_f32 v204, v68, v69
	v_cvt_pk_bf16_f32 v205, v70, v71
	v_cvt_pk_bf16_f32 v226, v72, v73
	v_cvt_pk_bf16_f32 v227, v74, v75
	v_cvt_pk_bf16_f32 v228, v76, v77
	v_cvt_pk_bf16_f32 v229, v78, v79
	v_permlane32_swap_b32_e32 v154, v156
	v_permlane32_swap_b32_e32 v155, v157
	v_permlane32_swap_b32_e32 v202, v204
	v_permlane32_swap_b32_e32 v203, v205
	v_permlane32_swap_b32_e32 v226, v228
	v_permlane32_swap_b32_e32 v227, v229
	v_permlane32_swap_b32_e32 v223, v224
	ds_read_b128 v[64:67], v170 offset:32768
	ds_read_b128 v[68:71], v170 offset:40960
	ds_read_b128 v[142:145], v171 offset:32768
	ds_read_b128 v[146:149], v171 offset:40960
	ds_read_b128 v[150:153], v172 offset:32768
	s_cmp_lt_u32 s2, s27
	s_cselect_b64 vcc, -1, 0
	s_waitcnt lgkmcnt(4)
	v_mfma_f32_32x32x16_bf16 v[80:95], v[64:67], v[126:129], 0
	s_waitcnt lgkmcnt(3)
	v_mfma_f32_32x32x16_bf16 v[64:79], v[68:71], v[126:129], 0
	s_waitcnt lgkmcnt(2)
	v_mfma_f32_32x32x16_bf16 v[80:95], v[142:145], v[122:125], v[80:95]
	ds_read_b128 v[142:145], v172 offset:40960
	s_waitcnt lgkmcnt(2)
	v_mfma_f32_32x32x16_bf16 v[64:79], v[146:149], v[122:125], v[64:79]
	ds_read_b128 v[146:149], v173 offset:32768
	s_waitcnt lgkmcnt(2)
	v_mfma_f32_32x32x16_bf16 v[80:95], v[150:153], v[118:121], v[80:95]
	ds_read_b128 v[150:153], v173 offset:40960
	s_waitcnt lgkmcnt(2)
	v_mfma_f32_32x32x16_bf16 v[64:79], v[142:145], v[118:121], v[64:79]
	ds_read_b128 v[142:145], v174 offset:32768
	s_waitcnt lgkmcnt(2)
	v_mfma_f32_32x32x16_bf16 v[80:95], v[146:149], v[114:117], v[80:95]
	ds_read_b128 v[146:149], v174 offset:40960
	s_waitcnt lgkmcnt(2)
	v_mfma_f32_32x32x16_bf16 v[64:79], v[150:153], v[114:117], v[64:79]
	ds_read_b128 v[150:153], v175 offset:32768
	s_waitcnt lgkmcnt(2)
	v_mfma_f32_32x32x16_bf16 v[80:95], v[142:145], v[110:113], v[80:95]
	ds_read_b128 v[142:145], v175 offset:40960
	s_waitcnt lgkmcnt(2)
	v_mfma_f32_32x32x16_bf16 v[64:79], v[146:149], v[110:113], v[64:79]
	ds_read_b128 v[146:149], v176 offset:32768
	s_waitcnt lgkmcnt(2)
	v_mfma_f32_32x32x16_bf16 v[80:95], v[150:153], v[106:109], v[80:95]
	ds_read_b128 v[150:153], v176 offset:40960
	s_waitcnt lgkmcnt(2)
	v_mfma_f32_32x32x16_bf16 v[64:79], v[142:145], v[106:109], v[64:79]
	ds_read_b128 v[142:145], v177 offset:32768
	s_waitcnt lgkmcnt(2)
	v_mfma_f32_32x32x16_bf16 v[80:95], v[146:149], v[102:105], v[80:95]
	ds_read_b128 v[146:149], v177 offset:40960
	s_waitcnt lgkmcnt(2)
	v_mfma_f32_32x32x16_bf16 v[64:79], v[150:153], v[102:105], v[64:79]
	s_waitcnt lgkmcnt(1)
	v_mfma_f32_32x32x16_bf16 v[80:95], v[142:145], v[98:101], v[80:95]
	s_waitcnt lgkmcnt(0)
	v_mfma_f32_32x32x16_bf16 v[64:79], v[146:149], v[98:101], v[64:79]
	ds_read_b128 v[142:145], v179
	ds_read_b128 v[146:149], v179 offset:4096
	ds_read_b128 v[150:153], v163
	s_waitcnt lgkmcnt(0)
	v_mfma_f32_32x32x16_bf16 v[80:95], v[142:145], v[150:153], v[80:95]
	v_mfma_f32_32x32x16_bf16 v[64:79], v[146:149], v[150:153], v[64:79]
	ds_read_b128 v[142:145], v181
	ds_read_b128 v[146:149], v181 offset:4096
	ds_read_b128 v[150:153], v163 offset:1024
	s_waitcnt lgkmcnt(0)
	v_mfma_f32_32x32x16_bf16 v[80:95], v[142:145], v[150:153], v[80:95]
	v_mfma_f32_32x32x16_bf16 v[64:79], v[146:149], v[150:153], v[64:79]
	ds_read_b128 v[142:145], v183
	ds_read_b128 v[146:149], v183 offset:4096
	ds_read_b128 v[150:153], v163 offset:2048
	s_waitcnt lgkmcnt(0)
	v_mfma_f32_32x32x16_bf16 v[80:95], v[142:145], v[150:153], v[80:95]
	v_mfma_f32_32x32x16_bf16 v[64:79], v[146:149], v[150:153], v[64:79]
	ds_read_b128 v[142:145], v185
	ds_read_b128 v[146:149], v185 offset:4096
	ds_read_b128 v[150:153], v163 offset:3072
	s_waitcnt lgkmcnt(0)
	v_mfma_f32_32x32x16_bf16 v[80:95], v[142:145], v[150:153], v[80:95]
	v_mfma_f32_32x32x16_bf16 v[64:79], v[146:149], v[150:153], v[64:79]
	s_nop 10
	v_cndmask_b32_e32 v218, v208, v80, vcc
	v_cndmask_b32_e32 v148, v208, v64, vcc
	v_cndmask_b32_e32 v149, v208, v65, vcc
	v_cndmask_b32_e32 v146, v208, v66, vcc
	v_cndmask_b32_e32 v147, v208, v67, vcc
	v_cndmask_b32_e32 v144, v208, v68, vcc
	v_cndmask_b32_e32 v145, v208, v69, vcc
	v_cndmask_b32_e32 v142, v208, v70, vcc
	v_cndmask_b32_e32 v143, v208, v71, vcc
	v_cndmask_b32_e32 v151, v208, v94, vcc
	v_cndmask_b32_e32 v94, v208, v72, vcc
	v_cndmask_b32_e32 v150, v208, v95, vcc
	v_cndmask_b32_e32 v95, v208, v73, vcc
	v_cndmask_b32_e32 v153, v208, v92, vcc
	v_cndmask_b32_e32 v92, v208, v74, vcc
	v_cndmask_b32_e32 v152, v208, v93, vcc
	v_cndmask_b32_e32 v93, v208, v75, vcc
	v_cndmask_b32_e32 v198, v208, v90, vcc
	v_cndmask_b32_e32 v90, v208, v76, vcc
	v_cndmask_b32_e32 v197, v208, v91, vcc
	v_cndmask_b32_e32 v91, v208, v77, vcc
	v_cndmask_b32_e32 v210, v208, v88, vcc
	v_cndmask_b32_e32 v88, v208, v78, vcc
	v_cndmask_b32_e32 v199, v208, v89, vcc
	v_cndmask_b32_e32 v89, v208, v79, vcc
	v_cndmask_b32_e32 v212, v208, v86, vcc
	v_cndmask_b32_e32 v213, v208, v85, vcc
	v_cndmask_b32_e32 v214, v208, v84, vcc
	v_cndmask_b32_e32 v211, v208, v87, vcc
	v_cndmask_b32_e32 v215, v208, v83, vcc
	v_cndmask_b32_e32 v216, v208, v82, vcc
	v_cndmask_b32_e32 v217, v208, v81, vcc
	v_cvt_pk_bf16_f32 v84, v233, v235
	v_cvt_pk_bf16_f32 v85, v231, v234
	v_mov_b32_e32 v86, v247
	v_mov_b32_e32 v87, v248
	s_nop 1
	v_permlane32_swap_b32_e32 v84, v86
	v_permlane32_swap_b32_e32 v85, v87
	ds_read_b64_tr_b16 v[138:139], v162 offset:0
	ds_read_b64_tr_b16 v[140:141], v162 offset:0x800
	ds_read_b64_tr_b16 v[230:231], v162 offset:0x1000
	ds_read_b64_tr_b16 v[232:233], v162 offset:0x1800
	ds_read_b64_tr_b16 v[234:235], v162 offset:0x2000
	ds_read_b64_tr_b16 v[236:237], v162 offset:0x2800
	ds_read_b64_tr_b16 v[238:239], v162 offset:0x3000
	ds_read_b64_tr_b16 v[240:241], v162 offset:0x3800
	s_waitcnt lgkmcnt(0)
	s_nop 0
	v_mfma_f32_32x32x16_bf16 v[0:15], v[84:87], v[138:141], v[0:15]
	ds_read_b64_tr_b16 v[138:139], v162 offset:0x200
	ds_read_b64_tr_b16 v[140:141], v162 offset:0xa00
	v_mfma_f32_32x32x16_bf16 v[0:15], v[154:157], v[230:233], v[0:15]
	ds_read_b64_tr_b16 v[230:231], v162 offset:0x1200
	ds_read_b64_tr_b16 v[232:233], v162 offset:0x1a00
	v_mfma_f32_32x32x16_bf16 v[0:15], v[202:205], v[234:237], v[0:15]
	ds_read_b64_tr_b16 v[234:235], v162 offset:0x2200
	ds_read_b64_tr_b16 v[236:237], v162 offset:0x2a00
	v_mfma_f32_32x32x16_bf16 v[0:15], v[226:229], v[238:241], v[0:15]
	ds_read_b64_tr_b16 v[238:239], v162 offset:0x3200
	ds_read_b64_tr_b16 v[240:241], v162 offset:0x3a00
	s_waitcnt lgkmcnt(0)
	v_mfma_f32_32x32x16_bf16 v[48:63], v[84:87], v[138:141], v[48:63]
	ds_read_b64_tr_b16 v[138:139], v162 offset:0x400
	ds_read_b64_tr_b16 v[140:141], v162 offset:0xc00
	v_mfma_f32_32x32x16_bf16 v[48:63], v[154:157], v[230:233], v[48:63]
	ds_read_b64_tr_b16 v[230:231], v162 offset:0x1400
	ds_read_b64_tr_b16 v[232:233], v162 offset:0x1c00
	v_mfma_f32_32x32x16_bf16 v[48:63], v[202:205], v[234:237], v[48:63]
	ds_read_b64_tr_b16 v[234:235], v162 offset:0x2400
	ds_read_b64_tr_b16 v[236:237], v162 offset:0x2c00
	v_mfma_f32_32x32x16_bf16 v[48:63], v[226:229], v[238:241], v[48:63]
	ds_read_b64_tr_b16 v[238:239], v162 offset:0x3400
	ds_read_b64_tr_b16 v[240:241], v162 offset:0x3c00
	s_waitcnt lgkmcnt(0)
	v_mfma_f32_32x32x16_bf16 v[32:47], v[84:87], v[138:141], v[32:47]
	ds_read_b64_tr_b16 v[138:139], v162 offset:0x600
	ds_read_b64_tr_b16 v[140:141], v162 offset:0xe00
	v_mfma_f32_32x32x16_bf16 v[32:47], v[154:157], v[230:233], v[32:47]
	ds_read_b64_tr_b16 v[230:231], v162 offset:0x1600
	ds_read_b64_tr_b16 v[232:233], v162 offset:0x1e00
	v_mfma_f32_32x32x16_bf16 v[32:47], v[202:205], v[234:237], v[32:47]
	ds_read_b64_tr_b16 v[234:235], v162 offset:0x2600
	ds_read_b64_tr_b16 v[236:237], v162 offset:0x2e00
	v_mfma_f32_32x32x16_bf16 v[32:47], v[226:229], v[238:241], v[32:47]
	ds_read_b64_tr_b16 v[238:239], v162 offset:0x3600
	ds_read_b64_tr_b16 v[240:241], v162 offset:0x3e00
	s_waitcnt lgkmcnt(0)
	v_mfma_f32_32x32x16_bf16 v[16:31], v[84:87], v[138:141], v[16:31]
	v_max_f32_e32 v84, v217, v217
	v_max_f32_e32 v85, v218, v218
	v_max_f32_e32 v84, v85, v84
	v_max3_f32 v84, v84, v216, v215
	v_max3_f32 v84, v84, v214, v213
	v_max3_f32 v84, v84, v212, v211
	v_max3_f32 v84, v84, v210, v199
	v_mfma_f32_32x32x16_bf16 v[16:31], v[154:157], v[230:233], v[16:31]
	v_max3_f32 v84, v84, v198, v197
	v_max3_f32 v84, v84, v153, v152
	v_max3_f32 v84, v84, v151, v150
	v_max3_f32 v84, v84, v148, v149
	v_max3_f32 v84, v84, v146, v147
	v_max3_f32 v84, v84, v144, v145
	v_max3_f32 v84, v84, v142, v143
	v_mfma_f32_32x32x16_bf16 v[16:31], v[202:205], v[234:237], v[16:31]
	v_max3_f32 v84, v84, v94, v95
	v_max3_f32 v84, v84, v92, v93
	v_max3_f32 v84, v84, v90, v91
	v_max3_f32 v84, v84, v88, v89
	v_mov_b32_e32 v85, v84
	s_nop 1
	v_permlane32_swap_b32_e32 v84, v85
	v_mfma_f32_32x32x16_bf16 v[16:31], v[226:229], v[238:241], v[16:31]
	v_max_f32_e32 v85, v85, v85
	v_max_f32_e32 v84, v84, v84
	v_max_f32_e32 v84, v84, v85
	v_sub_f32_e32 v85, v84, v165
	v_cmp_ge_f32_e32 vcc, s21, v85
	v_mov_b32_e32 v195, 1.0
	s_cmp_eq_u64 vcc, exec
	s_cbranch_scc0 .Latt1_751

.LBB0_752:
	v_readfirstlane_b32 s16, v134
	v_readfirstlane_b32 s17, v135
	s_lshl_b32 s3, s78, 14
	s_sub_u32 s16, s16, s3
	s_subb_u32 s17, s17, 0
	s_add_u32 s16, s16, 0x33040100
	s_addc_u32 s17, s17, 0
	s_lshl_b32 s3, s78, 10
	s_add_i32 m0, s3, 0x4000
	s_nop 0
	global_load_lds_dwordx4 v167, s[16:17]
	s_add_u32 s16, s16, 0x20000
	s_addc_u32 s17, s17, 0
	s_add_i32 m0, s3, 0x6000
	s_nop 0
	global_load_lds_dwordx4 v167, s[16:17]
	ds_read_b128 v[64:67], v170 offset:49152
	ds_read_b128 v[68:71], v170 offset:57344
	s_waitcnt lgkmcnt(1)
	v_mfma_f32_32x32x16_bf16 v[80:95], v[64:67], v[126:129], 0
	s_waitcnt lgkmcnt(0)
	v_mfma_f32_32x32x16_bf16 v[64:79], v[68:71], v[126:129], 0
	ds_read_b128 v[126:129], v171 offset:49152
	ds_read_b128 v[132:135], v171 offset:57344
	s_waitcnt lgkmcnt(1)
	v_mfma_f32_32x32x16_bf16 v[80:95], v[126:129], v[122:125], v[80:95]
	s_waitcnt lgkmcnt(0)
	v_mfma_f32_32x32x16_bf16 v[64:79], v[132:135], v[122:125], v[64:79]
	ds_read_b128 v[122:125], v172 offset:49152
	ds_read_b128 v[126:129], v172 offset:57344
	s_waitcnt lgkmcnt(1)
	v_mfma_f32_32x32x16_bf16 v[80:95], v[122:125], v[118:121], v[80:95]
	s_waitcnt lgkmcnt(0)
	v_mfma_f32_32x32x16_bf16 v[64:79], v[126:129], v[118:121], v[64:79]
	ds_read_b128 v[118:121], v173 offset:49152
	ds_read_b128 v[122:125], v173 offset:57344
	s_waitcnt lgkmcnt(1)
	v_mfma_f32_32x32x16_bf16 v[80:95], v[118:121], v[114:117], v[80:95]
	s_waitcnt lgkmcnt(0)
	v_mfma_f32_32x32x16_bf16 v[64:79], v[122:125], v[114:117], v[64:79]
	ds_read_b128 v[114:117], v174 offset:49152
	ds_read_b128 v[118:121], v174 offset:57344
	s_waitcnt lgkmcnt(1)
	v_mfma_f32_32x32x16_bf16 v[80:95], v[114:117], v[110:113], v[80:95]
	s_waitcnt lgkmcnt(0)
	v_mfma_f32_32x32x16_bf16 v[64:79], v[118:121], v[110:113], v[64:79]
	ds_read_b128 v[110:113], v175 offset:49152
	ds_read_b128 v[114:117], v175 offset:57344
	s_waitcnt lgkmcnt(1)
	v_mfma_f32_32x32x16_bf16 v[80:95], v[110:113], v[106:109], v[80:95]
	s_waitcnt lgkmcnt(0)
	v_mfma_f32_32x32x16_bf16 v[64:79], v[114:117], v[106:109], v[64:79]
	ds_read_b128 v[106:109], v176 offset:49152
	ds_read_b128 v[110:113], v176 offset:57344
	s_waitcnt lgkmcnt(1)
	v_mfma_f32_32x32x16_bf16 v[80:95], v[106:109], v[102:105], v[80:95]
	s_waitcnt lgkmcnt(0)
	v_mfma_f32_32x32x16_bf16 v[64:79], v[110:113], v[102:105], v[64:79]
	ds_read_b128 v[102:105], v177 offset:49152
	ds_read_b128 v[106:109], v177 offset:57344
	s_waitcnt lgkmcnt(1)
	v_mfma_f32_32x32x16_bf16 v[80:95], v[102:105], v[98:101], v[80:95]
	s_waitcnt lgkmcnt(0)
	v_mfma_f32_32x32x16_bf16 v[64:79], v[106:109], v[98:101], v[64:79]
	ds_read_b128 v[98:101], v189
	ds_read_b128 v[102:105], v163
	ds_read_b128 v[106:109], v189 offset:4096
	ds_read_b128 v[110:113], v163 offset:1024
	s_waitcnt lgkmcnt(2)
	v_mfma_f32_32x32x16_bf16 v[80:95], v[98:101], v[102:105], v[80:95]
	s_waitcnt lgkmcnt(1)
	v_mfma_f32_32x32x16_bf16 v[64:79], v[106:109], v[102:105], v[64:79]
	ds_read_b128 v[98:101], v190
	ds_read_b128 v[102:105], v190 offset:4096
	s_waitcnt lgkmcnt(1)
	v_mfma_f32_32x32x16_bf16 v[80:95], v[98:101], v[110:113], v[80:95]
	ds_read_b128 v[98:101], v191
	ds_read_b128 v[106:109], v163 offset:2048
	ds_read_b128 v[114:117], v191 offset:4096
	ds_read_b128 v[118:121], v163 offset:3072
	s_waitcnt lgkmcnt(4)
	v_mfma_f32_32x32x16_bf16 v[64:79], v[102:105], v[110:113], v[64:79]
	v_exp_f32_e32 v110, v146
	v_exp_f32_e32 v111, v147
	v_exp_f32_e32 v112, v144
	v_exp_f32_e32 v113, v145
	s_waitcnt lgkmcnt(2)
	v_mfma_f32_32x32x16_bf16 v[80:95], v[98:101], v[106:109], v[80:95]
	ds_read_b128 v[98:101], v192
	ds_read_b128 v[122:125], v192 offset:4096
	s_waitcnt lgkmcnt(3)
	v_mfma_f32_32x32x16_bf16 v[64:79], v[114:117], v[106:109], v[64:79]
	v_exp_f32_e32 v108, v148
	v_exp_f32_e32 v109, v149
	v_exp_f32_e32 v114, v140
	v_exp_f32_e32 v115, v141
	v_exp_f32_e32 v116, v138
	v_exp_f32_e32 v117, v139
	s_waitcnt lgkmcnt(1)
	v_mfma_f32_32x32x16_bf16 v[80:95], v[98:101], v[118:121], v[80:95]
	v_cvt_pk_bf16_f32 v100, v220, v222
	v_cvt_pk_bf16_f32 v101, v218, v221
	v_cvt_pk_bf16_f32 v102, v216, v219
	v_cvt_pk_bf16_f32 v103, v215, v217
	v_cvt_pk_bf16_f32 v104, v212, v214
	v_cvt_pk_bf16_f32 v105, v210, v213
	v_cvt_pk_bf16_f32 v106, v198, v211
	s_waitcnt lgkmcnt(0)
	v_mfma_f32_32x32x16_bf16 v[64:79], v[122:125], v[118:121], v[64:79]
	s_nop 9
	v_cndmask_b32_e64 v98, v80, v208, s[96:97]
	v_exp_f32_e32 v118, v152
	v_exp_f32_e32 v119, v153
	v_exp_f32_e32 v120, v150
	v_exp_f32_e32 v121, v151
	v_exp_f32_e32 v122, v142
	v_exp_f32_e32 v123, v143
	v_cndmask_b32_e64 v80, v76, v208, s[96:97]
	v_cndmask_b32_e64 v76, v77, v208, s[96:97]
	v_cndmask_b32_e64 v77, v64, v208, s[96:97]
	v_add_f32_e32 v64, 0, v220
	v_add_f32_e32 v64, v222, v64
	v_add_f32_e32 v64, v218, v64
	v_add_f32_e32 v64, v221, v64
	v_add_f32_e32 v64, v216, v64
	v_add_f32_e32 v64, v219, v64
	v_add_f32_e32 v64, v215, v64
	v_add_f32_e32 v64, v217, v64
	v_add_f32_e32 v64, v212, v64
	v_add_f32_e32 v64, v214, v64
	v_add_f32_e32 v64, v210, v64
	v_add_f32_e32 v64, v213, v64
	v_add_f32_e32 v64, v198, v64
	v_add_f32_e32 v64, v211, v64
	v_add_f32_e32 v64, v197, v64
	v_add_f32_e32 v64, v199, v64
	v_add_f32_e32 v64, v108, v64
	v_add_f32_e32 v64, v109, v64
	v_add_f32_e32 v64, v110, v64
	v_add_f32_e32 v64, v111, v64
	v_add_f32_e32 v64, v112, v64
	v_add_f32_e32 v64, v113, v64
	v_add_f32_e32 v64, v114, v64
	v_add_f32_e32 v64, v115, v64
	v_add_f32_e32 v64, v116, v64
	v_add_f32_e32 v64, v117, v64
	v_add_f32_e32 v64, v118, v64
	v_add_f32_e32 v64, v119, v64
	v_add_f32_e32 v64, v120, v64
	v_add_f32_e32 v64, v121, v64
	v_add_f32_e32 v64, v122, v64
	v_add_f32_e32 v64, v123, v64
	v_cndmask_b32_e64 v99, v65, v208, s[96:97]
	v_mov_b32_e32 v65, v64
	v_cndmask_b32_e64 v94, v94, v208, s[96:97]
	v_cndmask_b32_e64 v95, v95, v208, s[96:97]
	v_cndmask_b32_e64 v92, v92, v208, s[96:97]
	v_cndmask_b32_e64 v93, v93, v208, s[96:97]
	v_cndmask_b32_e64 v90, v90, v208, s[96:97]
	v_cndmask_b32_e64 v91, v91, v208, s[96:97]
	v_cndmask_b32_e64 v88, v88, v208, s[96:97]
	v_cndmask_b32_e64 v89, v89, v208, s[96:97]
	v_cndmask_b32_e64 v86, v86, v208, s[96:97]
	v_cndmask_b32_e64 v87, v87, v208, s[96:97]
	v_cndmask_b32_e64 v84, v84, v208, s[96:97]
	v_cndmask_b32_e64 v85, v85, v208, s[96:97]
	v_cndmask_b32_e64 v82, v82, v208, s[96:97]
	v_cndmask_b32_e64 v83, v83, v208, s[96:97]
	v_cndmask_b32_e64 v81, v81, v208, s[96:97]
	v_cndmask_b32_e64 v78, v78, v208, s[96:97]
	v_cndmask_b32_e64 v79, v79, v208, s[96:97]
	v_cndmask_b32_e64 v74, v74, v208, s[96:97]
	v_cndmask_b32_e64 v75, v75, v208, s[96:97]
	v_cndmask_b32_e64 v72, v72, v208, s[96:97]
	v_cndmask_b32_e64 v73, v73, v208, s[96:97]
	v_cndmask_b32_e64 v70, v70, v208, s[96:97]
	v_cndmask_b32_e64 v71, v71, v208, s[96:97]
	v_cndmask_b32_e64 v68, v68, v208, s[96:97]
	v_cndmask_b32_e64 v69, v69, v208, s[96:97]
	v_cndmask_b32_e64 v66, v66, v208, s[96:97]
	v_cndmask_b32_e64 v67, v67, v208, s[96:97]
	v_permlane32_swap_b32_e32 v64, v65
	v_permlane32_swap_b32_e32 v100, v102
	v_permlane32_swap_b32_e32 v101, v103
	v_cvt_pk_bf16_f32 v107, v197, v199
	v_cvt_pk_bf16_f32 v108, v108, v109
	v_cvt_pk_bf16_f32 v109, v110, v111
	v_cvt_pk_bf16_f32 v110, v112, v113
	v_cvt_pk_bf16_f32 v111, v114, v115
	v_cvt_pk_bf16_f32 v112, v116, v117
	v_cvt_pk_bf16_f32 v113, v118, v119
	v_cvt_pk_bf16_f32 v114, v120, v121
	v_cvt_pk_bf16_f32 v115, v122, v123
	v_permlane32_swap_b32_e32 v104, v106
	v_permlane32_swap_b32_e32 v105, v107
	v_permlane32_swap_b32_e32 v108, v110
	v_permlane32_swap_b32_e32 v109, v111
	v_permlane32_swap_b32_e32 v112, v114
	v_permlane32_swap_b32_e32 v113, v115
	ds_read_b64_tr_b16 v[116:117], v164 offset:0
	ds_read_b64_tr_b16 v[118:119], v164 offset:0x800
	ds_read_b64_tr_b16 v[120:121], v164 offset:0x1000
	ds_read_b64_tr_b16 v[122:123], v164 offset:0x1800
	ds_read_b64_tr_b16 v[124:125], v164 offset:0x2000
	ds_read_b64_tr_b16 v[126:127], v164 offset:0x2800
	ds_read_b64_tr_b16 v[132:133], v164 offset:0x3000
	ds_read_b64_tr_b16 v[134:135], v164 offset:0x3800
	s_waitcnt lgkmcnt(0)
	s_nop 0
	v_mfma_f32_32x32x16_bf16 v[0:15], v[100:103], v[116:119], v[0:15]
	ds_read_b64_tr_b16 v[116:117], v164 offset:0x200
	ds_read_b64_tr_b16 v[118:119], v164 offset:0xa00
	v_mfma_f32_32x32x16_bf16 v[0:15], v[104:107], v[120:123], v[0:15]
	ds_read_b64_tr_b16 v[120:121], v164 offset:0x1200
	ds_read_b64_tr_b16 v[122:123], v164 offset:0x1a00
	v_mfma_f32_32x32x16_bf16 v[0:15], v[108:111], v[124:127], v[0:15]
	ds_read_b64_tr_b16 v[124:125], v164 offset:0x2200
	ds_read_b64_tr_b16 v[126:127], v164 offset:0x2a00
	v_mfma_f32_32x32x16_bf16 v[0:15], v[112:115], v[132:135], v[0:15]
	ds_read_b64_tr_b16 v[132:133], v164 offset:0x3200
	ds_read_b64_tr_b16 v[134:135], v164 offset:0x3a00
	s_waitcnt lgkmcnt(0)
	v_mfma_f32_32x32x16_bf16 v[48:63], v[100:103], v[116:119], v[48:63]
	ds_read_b64_tr_b16 v[116:117], v164 offset:0x400
	ds_read_b64_tr_b16 v[118:119], v164 offset:0xc00
	v_mfma_f32_32x32x16_bf16 v[48:63], v[104:107], v[120:123], v[48:63]
	ds_read_b64_tr_b16 v[120:121], v164 offset:0x1400
	ds_read_b64_tr_b16 v[122:123], v164 offset:0x1c00
	v_mfma_f32_32x32x16_bf16 v[48:63], v[108:111], v[124:127], v[48:63]
	ds_read_b64_tr_b16 v[124:125], v164 offset:0x2400
	ds_read_b64_tr_b16 v[126:127], v164 offset:0x2c00
	v_mfma_f32_32x32x16_bf16 v[48:63], v[112:115], v[132:135], v[48:63]
	ds_read_b64_tr_b16 v[132:133], v164 offset:0x3400
	ds_read_b64_tr_b16 v[134:135], v164 offset:0x3c00
	s_waitcnt lgkmcnt(0)
	v_mfma_f32_32x32x16_bf16 v[32:47], v[100:103], v[116:119], v[32:47]
	ds_read_b64_tr_b16 v[116:117], v164 offset:0x600
	ds_read_b64_tr_b16 v[118:119], v164 offset:0xe00
	v_mfma_f32_32x32x16_bf16 v[32:47], v[104:107], v[120:123], v[32:47]
	ds_read_b64_tr_b16 v[120:121], v164 offset:0x1600
	ds_read_b64_tr_b16 v[122:123], v164 offset:0x1e00
	v_mfma_f32_32x32x16_bf16 v[32:47], v[108:111], v[124:127], v[32:47]
	ds_read_b64_tr_b16 v[124:125], v164 offset:0x2600
	ds_read_b64_tr_b16 v[126:127], v164 offset:0x2e00
	v_mfma_f32_32x32x16_bf16 v[32:47], v[112:115], v[132:135], v[32:47]
	ds_read_b64_tr_b16 v[132:133], v164 offset:0x3600
	ds_read_b64_tr_b16 v[134:135], v164 offset:0x3e00
	s_waitcnt lgkmcnt(0)
	v_mfma_f32_32x32x16_bf16 v[16:31], v[100:103], v[116:119], v[16:31]
	v_max_f32_e32 v100, v81, v81
	v_max_f32_e32 v101, v98, v98
	v_max_f32_e32 v100, v101, v100
	v_max3_f32 v100, v100, v82, v83
	v_max3_f32 v100, v100, v84, v85
	v_max3_f32 v100, v100, v86, v87
	v_max3_f32 v100, v100, v88, v89
	v_mfma_f32_32x32x16_bf16 v[16:31], v[104:107], v[120:123], v[16:31]
	v_max3_f32 v100, v100, v90, v91
	v_max3_f32 v100, v100, v92, v93
	v_max3_f32 v100, v100, v94, v95
	v_max3_f32 v100, v100, v77, v99
	v_max3_f32 v100, v100, v66, v67
	v_max3_f32 v100, v100, v68, v69
	v_max3_f32 v100, v100, v70, v71
	v_mfma_f32_32x32x16_bf16 v[16:31], v[108:111], v[124:127], v[16:31]
	v_max3_f32 v100, v100, v72, v73
	v_max3_f32 v100, v100, v74, v75
	v_max3_f32 v100, v100, v80, v76
	v_max3_f32 v100, v100, v78, v79
	v_mov_b32_e32 v101, v100
	s_nop 1
	v_permlane32_swap_b32_e32 v100, v101
	v_mfma_f32_32x32x16_bf16 v[16:31], v[112:115], v[132:135], v[16:31]
	v_max_f32_e32 v101, v101, v101
	v_max_f32_e32 v100, v100, v100
	v_max_f32_e32 v101, v100, v101
	v_sub_f32_e32 v100, v101, v165
	v_cmp_ge_f32_e32 vcc, s21, v100
	v_mov_b32_e32 v100, 1.0
	s_cmp_eq_u64 vcc, exec
	s_cbranch_scc0 .LBB0_787
.LBB0_753:
	v_cmp_gt_f32_e32 vcc, 1.0, v100
	s_waitcnt vmcnt(0)
	s_barrier
	s_cbranch_vccz .LBB0_757
	s_and_saveexec_b64 s[0:1], s[38:39]
	ds_write_b32 v160, v100 offset:128
	s_or_b64 exec, exec, s[0:1]
	s_waitcnt lgkmcnt(0)
	v_add_u32_e32 v101, s19, v130
	ds_read_b128 v[102:105], v101 offset:224
	ds_read_b128 v[106:109], v101 offset:192
	ds_read_b128 v[110:113], v101 offset:160
	ds_read_b128 v[114:117], v101 offset:128
	s_waitcnt lgkmcnt(3)
	v_pk_mul_f32 v[12:13], v[12:13], v[102:103]
	s_waitcnt lgkmcnt(2)
	v_pk_mul_f32 v[8:9], v[8:9], v[106:107]
	s_waitcnt lgkmcnt(1)
	v_pk_mul_f32 v[4:5], v[4:5], v[110:111]
	v_pk_mul_f32 v[14:15], v[14:15], v[104:105]
	v_pk_mul_f32 v[10:11], v[10:11], v[108:109]
	v_pk_mul_f32 v[6:7], v[6:7], v[112:113]
	s_waitcnt lgkmcnt(0)
	v_pk_mul_f32 v[2:3], v[2:3], v[116:117]
	v_pk_mul_f32 v[0:1], v[0:1], v[114:115]
	v_pk_mul_f32 v[60:61], v[60:61], v[102:103]
	v_pk_mul_f32 v[56:57], v[56:57], v[106:107]
	v_pk_mul_f32 v[52:53], v[52:53], v[110:111]
	v_pk_mul_f32 v[62:63], v[62:63], v[104:105]
	v_pk_mul_f32 v[58:59], v[58:59], v[108:109]
	v_pk_mul_f32 v[54:55], v[54:55], v[112:113]
	v_pk_mul_f32 v[50:51], v[50:51], v[116:117]
	v_pk_mul_f32 v[48:49], v[48:49], v[114:115]
	v_pk_mul_f32 v[44:45], v[44:45], v[102:103]
	v_pk_mul_f32 v[40:41], v[40:41], v[106:107]
	v_pk_mul_f32 v[36:37], v[36:37], v[110:111]
	v_pk_mul_f32 v[46:47], v[46:47], v[104:105]
	v_pk_mul_f32 v[42:43], v[42:43], v[108:109]
	v_pk_mul_f32 v[38:39], v[38:39], v[112:113]
	v_pk_mul_f32 v[34:35], v[34:35], v[116:117]
	v_pk_mul_f32 v[32:33], v[32:33], v[114:115]
	v_pk_mul_f32 v[28:29], v[28:29], v[102:103]
	v_pk_mul_f32 v[24:25], v[24:25], v[106:107]
	v_pk_mul_f32 v[20:21], v[20:21], v[110:111]
	v_pk_mul_f32 v[30:31], v[30:31], v[104:105]
	v_pk_mul_f32 v[26:27], v[26:27], v[108:109]
	v_pk_mul_f32 v[22:23], v[22:23], v[112:113]
	v_pk_mul_f32 v[18:19], v[18:19], v[116:117]
	v_pk_mul_f32 v[16:17], v[16:17], v[114:115]
